# conv-act epilogue: tanh-gelu polynomial constants folded (5 VALU -> 3 per element, same f32 math)
# speedup vs baseline: 1.0021x; 1.0021x over previous
;     DI void operator()(const AccT& acc, const Unit& u, int wr, int wc, int fr, int fq) const {
;     ...
;             const int col = u.pn * 256 + bj * 128 + wc * 32 + 8 * fq;
;             f32x4 w0[2], w1[2], w2[2], cb[2];
; #pragma unroll
;             for (int hh = 0; hh < 2; ++hh) { w0[hh] = *(const f32x4*)(conv_w + col + 4 * hh); w1[hh] = *(const f32x4*)(conv_w + FF + col + 4 * hh); w2[hh] = *(const f32x4*)(conv_w + 2 * FF + col + 4 * hh); cb[hh] = *(const f32x4*)(conv_b + col + 4 * hh); }
; #pragma unroll
;             for (int aim = 0; aim < 4; ++aim) { const int ai = aim >> 1, mb = (aim & 1) * 2;
;                 u32x4 a0[4], a1[4], a2[4];
; #pragma unroll
;                 for (int m = mb; m < mb + 2; ++m) {
;                     const int row = rowbase + ai * 128 + m * 16; const int sq = row & (SEQ - 1);
;                     const bf16_t* pa = A + (size_t)row * FF + col;
;                     a0[m] = *(const u32x4*)pa;
;                     a1[m] = *(const u32x4*)(pa - (sq >= 1 ? FF : 0));
;                     a2[m] = *(const u32x4*)(pa - (sq >= 2 ? 2 * FF : 0));
;                 }
; #pragma unroll
;                 for (int m = mb; m < mb + 2; ++m) {
;                     const int row = rowbase + ai * 128 + m * 16; const int sq = row & (SEQ - 1);
;                     const float k1 = sq >= 1 ? 1.0f : 0.0f, k2 = sq >= 2 ? 1.0f : 0.0f;
;                     const u32x4 x0 = a0[m], x1 = a1[m], x2 = a2[m];
;                     const float f0[8] = {bflo(x0.x), bfhi(x0.x), bflo(x0.y), bfhi(x0.y), bflo(x0.z), bfhi(x0.z), bflo(x0.w), bfhi(x0.w)};
;                     const float f1[8] = {bflo(x1.x), bfhi(x1.x), bflo(x1.y), bfhi(x1.y), bflo(x1.z), bfhi(x1.z), bflo(x1.w), bfhi(x1.w)};
;                     const float f2[8] = {bflo(x2.x), bfhi(x2.x), bflo(x2.y), bfhi(x2.y), bflo(x2.z), bfhi(x2.z), bflo(x2.w), bfhi(x2.w)};
;                     f32x4 o0, o1;
; #pragma unroll
;                     for (int j = 0; j < 4; ++j) {
;                         const float c0 = cb[0][j] + w0[0][j] * f0[j] + k1 * (w1[0][j] * f1[j]) + k2 * (w2[0][j] * f2[j]);
;                         const float c1 = cb[1][j] + w0[1][j] * f0[4 + j] + k1 * (w1[1][j] * f1[4 + j]) + k2 * (w2[1][j] * f2[4 + j]);
;                         o0[j] = gelu_tanh(c0) * acc[ai][bj][m][0][j]; o1[j] = gelu_tanh(c1) * acc[ai][bj][m][1][j];
.LBB0_548:
	v_mov_b32_e32 v252, 0x3dd2d3e7
	v_lshl_or_b32 v192, s0, 8, v206
	v_ashrrev_i32_e32 v193, 31, v192
	v_lshlrev_b64 v[198:199], 1, v[192:193]
	v_lshl_add_u32 v212, s2, 8, v185
	v_lshl_add_u64 v[204:205], s[12:13], 0, v[198:199]
	v_and_b32_e32 v108, 0x1fcf, v212
	v_mad_i64_i32 v[104:105], s[0:1], v212, s60, v[204:205]
	v_cmp_eq_u32_e32 vcc, 0, v108
	v_cmp_lt_u32_e64 s[0:1], 1, v108
	v_readlane_b32 s64, v254, 0
	v_cndmask_b32_e64 v195, -1, 0, vcc
	v_cndmask_b32_e64 v194, v210, 0, vcc
	v_cndmask_b32_e64 v197, 0, -1, s[0:1]
	v_cndmask_b32_e64 v196, 0, v211, s[0:1]
	v_lshlrev_b64 v[102:103], 2, v[192:193]
	v_readlane_b32 s65, v254, 1
	v_readlane_b32 s66, v254, 2
	v_readlane_b32 s67, v254, 3
	v_lshl_add_u64 v[106:107], v[104:105], 0, v[194:195]
	global_load_dwordx4 v[200:203], v[104:105], off
	global_load_dwordx4 v[214:217], v[106:107], off
	v_lshl_add_u64 v[104:105], v[104:105], 0, v[196:197]
	v_lshl_add_u64 v[188:189], s[64:65], 0, v[102:103]
	v_lshl_add_u64 v[190:191], s[66:67], 0, v[102:103]
	global_load_dwordx4 v[218:221], v[104:105], off
	global_load_dwordx4 v[118:121], v[188:189], off
	global_load_dwordx4 v[122:125], v[190:191], off
	v_lshl_add_u64 v[106:107], s[20:21], 0, v[102:103]
	v_lshl_add_u64 v[110:111], s[22:23], 0, v[102:103]
	global_load_dwordx4 v[126:129], v[106:107], off
	global_load_dwordx4 v[130:133], v[110:111], off
	global_load_dwordx4 v[102:105], v[188:189], off offset:16
	s_nop 0
	global_load_dwordx4 v[106:109], v[106:107], off offset:16
	s_nop 0
	global_load_dwordx4 v[110:113], v[110:111], off offset:16
	s_nop 0
	global_load_dwordx4 v[114:117], v[190:191], off offset:16
	v_or_b32_e32 v193, 16, v212
	v_cndmask_b32_e64 v184, 0, 1.0, s[0:1]
	v_mad_i64_i32 v[162:163], s[0:1], v193, s60, v[204:205]
	v_cndmask_b32_e64 v186, 1.0, 0, vcc
	v_add_co_u32_e32 v164, vcc, s61, v162
	v_readlane_b32 s68, v254, 4
	s_nop 0
	v_addc_co_u32_e32 v165, vcc, -1, v163, vcc
	v_add_co_u32_e32 v222, vcc, s62, v162
	v_readlane_b32 s69, v254, 5
	s_nop 0
	v_addc_co_u32_e32 v223, vcc, -1, v163, vcc
	global_load_dwordx4 v[170:173], v[162:163], off
	global_load_dwordx4 v[166:169], v[164:165], off offset:-3072
	s_nop 0
	global_load_dwordx4 v[162:165], v[222:223], off offset:-2048
	v_readlane_b32 s70, v254, 6
	v_readlane_b32 s71, v254, 7
	s_waitcnt vmcnt(0)
	v_lshlrev_b32_e32 v222, 16, v200
	v_and_b32_e32 v223, 0xffff0000, v200
	v_lshlrev_b32_e32 v200, 16, v201
	v_and_b32_e32 v201, 0xffff0000, v201
	v_lshlrev_b32_e32 v224, 16, v214
	v_and_b32_e32 v225, 0xffff0000, v214
	v_lshlrev_b32_e32 v214, 16, v215
	v_and_b32_e32 v215, 0xffff0000, v215
	v_lshlrev_b32_e32 v226, 16, v218
	v_and_b32_e32 v227, 0xffff0000, v218
	v_pk_fma_f32 v[222:223], v[118:119], v[222:223], v[122:123]
	v_lshlrev_b32_e32 v218, 16, v219
	v_and_b32_e32 v219, 0xffff0000, v219
	v_pk_fma_f32 v[200:201], v[120:121], v[200:201], v[124:125]
	v_pk_mul_f32 v[224:225], v[126:127], v[224:225]
	v_pk_mul_f32 v[214:215], v[128:129], v[214:215]
	v_pk_mul_f32 v[226:227], v[130:131], v[226:227]
	v_pk_mul_f32 v[218:219], v[132:133], v[218:219]
	v_pk_fma_f32 v[222:223], v[186:187], v[224:225], v[222:223] op_sel_hi:[0,1,1]
	v_pk_fma_f32 v[200:201], v[186:187], v[214:215], v[200:201] op_sel_hi:[0,1,1]
	v_pk_fma_f32 v[214:215], v[184:185], v[226:227], v[222:223] op_sel_hi:[0,1,1]
	v_pk_fma_f32 v[200:201], v[184:185], v[218:219], v[200:201] op_sel_hi:[0,1,1]
	v_mul_f32_e32 v213, v214, v214
	v_mul_f32_e32 v218, v215, v215
	v_mul_f32_e32 v219, v200, v200
	v_mul_f32_e32 v222, v201, v201
	v_fmaak_f32 v213, v252, v213, 0x40135761
	v_fmaak_f32 v218, v252, v218, 0x40135761
	v_fmaak_f32 v219, v252, v219, 0x40135761
	v_fmaak_f32 v222, v252, v222, 0x40135761
	v_mul_f32_e32 v213, v214, v213
	v_mul_f32_e32 v218, v215, v218
	v_mul_f32_e32 v219, v200, v219
	v_mul_f32_e32 v222, v201, v222
	v_exp_f32_e32 v213, v213
	v_exp_f32_e32 v218, v218
	v_exp_f32_e32 v219, v219
	v_exp_f32_e32 v222, v222
	v_add_f32_e32 v213, 1.0, v213
	v_add_f32_e32 v223, 1.0, v218
	v_add_f32_e32 v224, 1.0, v219
	v_add_f32_e32 v225, 1.0, v222
	v_rcp_f32_e32 v218, v213
	v_rcp_f32_e32 v219, v223
	v_rcp_f32_e32 v222, v224
	v_rcp_f32_e32 v223, v225
	v_pk_fma_f32 v[214:215], v[214:215], v[218:219], v[214:215] neg_lo:[1,0,0] neg_hi:[1,0,0]
	s_nop 0
	v_pk_mul_f32 v[158:159], v[158:159], v[214:215]
	v_pk_fma_f32 v[200:201], v[200:201], v[222:223], v[200:201] neg_lo:[1,0,0] neg_hi:[1,0,0]
	v_lshlrev_b32_e32 v214, 16, v216
	v_pk_mul_f32 v[160:161], v[160:161], v[200:201]
	v_lshlrev_b32_e32 v200, 16, v202
	v_and_b32_e32 v201, 0xffff0000, v202
	v_and_b32_e32 v215, 0xffff0000, v216
	v_lshlrev_b32_e32 v218, 16, v220
	v_and_b32_e32 v219, 0xffff0000, v220
	v_pk_fma_f32 v[200:201], v[102:103], v[200:201], v[114:115]
	v_pk_mul_f32 v[214:215], v[106:107], v[214:215]
	v_cvt_pk_bf16_f32 v158, v158, v159
	v_pk_fma_f32 v[200:201], v[186:187], v[214:215], v[200:201] op_sel_hi:[0,1,1]
	v_pk_mul_f32 v[214:215], v[110:111], v[218:219]
	v_lshlrev_b32_e32 v216, 16, v221
	v_pk_fma_f32 v[200:201], v[184:185], v[214:215], v[200:201] op_sel_hi:[0,1,1]
	v_mul_f32_e32 v159, v200, v200
	v_fmaak_f32 v159, v252, v159, 0x40135761
	v_mul_f32_e32 v159, v200, v159
	v_exp_f32_e32 v202, v159
	v_mul_f32_e32 v159, v201, v201
	v_fmaak_f32 v159, v252, v159, 0x40135761
	v_mul_f32_e32 v159, v201, v159
	v_exp_f32_e32 v213, v159
	v_cvt_pk_bf16_f32 v159, v160, v161
	v_add_f32_e32 v160, 1.0, v202
	v_lshlrev_b32_e32 v202, 16, v203
	v_and_b32_e32 v203, 0xffff0000, v203
	v_lshlrev_b32_e32 v214, 16, v217
	v_and_b32_e32 v215, 0xffff0000, v217
	v_and_b32_e32 v217, 0xffff0000, v221
	v_pk_fma_f32 v[202:203], v[104:105], v[202:203], v[116:117]
	v_pk_mul_f32 v[214:215], v[108:109], v[214:215]
; DI float bflo(unsigned w) { return __uint_as_float(w << 16); }
;     DI void operator()(const AccT& acc, const Unit& u, int wr, int wc, int fr, int fq) const {
;     ...
;             for (int hh = 0; hh < 2; ++hh) { w0[hh] = *(const f32x4*)(conv_w + col + 4 * hh); w1[hh] = *(const f32x4*)(conv_w + FF + col + 4 * hh); w2[hh] = *(const f32x4*)(conv_w + 2 * FF + col + 4 * hh); cb[hh] = *(const f32x4*)(conv_b + col + 4 * hh); }
; #pragma unroll
;             for (int aim = 0; aim < 4; ++aim) { const int ai = aim >> 1, mb = (aim & 1) * 2;
;                 u32x4 a0[4], a1[4], a2[4];
; #pragma unroll
;                 for (int m = mb; m < mb + 2; ++m) {
;                     const int row = rowbase + ai * 128 + m * 16; const int sq = row & (SEQ - 1);
;                     const bf16_t* pa = A + (size_t)row * FF + col;
;                     a0[m] = *(const u32x4*)pa;
;                     a1[m] = *(const u32x4*)(pa - (sq >= 1 ? FF : 0));
;                     a2[m] = *(const u32x4*)(pa - (sq >= 2 ? 2 * FF : 0));
;                 }
; #pragma unroll
;                 for (int m = mb; m < mb + 2; ++m) {
;                     const int row = rowbase + ai * 128 + m * 16; const int sq = row & (SEQ - 1);
;                     const float k1 = sq >= 1 ? 1.0f : 0.0f, k2 = sq >= 2 ? 1.0f : 0.0f;
;                     const u32x4 x0 = a0[m], x1 = a1[m], x2 = a2[m];
;                     const float f0[8] = {bflo(x0.x), bfhi(x0.x), bflo(x0.y), bfhi(x0.y), bflo(x0.z), bfhi(x0.z), bflo(x0.w), bfhi(x0.w)};
;                     const float f1[8] = {bflo(x1.x), bfhi(x1.x), bflo(x1.y), bfhi(x1.y), bflo(x1.z), bfhi(x1.z), bflo(x1.w), bfhi(x1.w)};
;                     const float f2[8] = {bflo(x2.x), bfhi(x2.x), bflo(x2.y), bfhi(x2.y), bflo(x2.z), bfhi(x2.z), bflo(x2.w), bfhi(x2.w)};
;                     f32x4 o0, o1;
; #pragma unroll
;                     for (int j = 0; j < 4; ++j) {
;                         const float c0 = cb[0][j] + w0[0][j] * f0[j] + k1 * (w1[0][j] * f1[j]) + k2 * (w2[0][j] * f2[j]);
;                         const float c1 = cb[1][j] + w0[1][j] * f0[4 + j] + k1 * (w1[1][j] * f1[4 + j]) + k2 * (w2[1][j] * f2[4 + j]);
;                         o0[j] = gelu_tanh(c0) * acc[ai][bj][m][0][j]; o1[j] = gelu_tanh(c1) * acc[ai][bj][m][1][j];
;                     }
;                     *(u32x4*)(ACT + (size_t)row * FF + col) = pack8(o0, o1);
	v_add_f32_e32 v161, 1.0, v213
	v_pk_fma_f32 v[202:203], v[186:187], v[214:215], v[202:203] op_sel_hi:[0,1,1]
	v_pk_mul_f32 v[214:215], v[112:113], v[216:217]
	v_rcp_f32_e32 v160, v160
	v_pk_fma_f32 v[202:203], v[184:185], v[214:215], v[202:203] op_sel_hi:[0,1,1]
	v_mul_f32_e32 v213, v202, v202
	v_fmaak_f32 v213, v252, v213, 0x40135761
	v_mul_f32_e32 v214, v203, v203
	v_mul_f32_e32 v213, v202, v213
	v_fmaak_f32 v214, v252, v214, 0x40135761
	v_mul_f32_e32 v214, v203, v214
	v_exp_f32_e32 v213, v213
	v_exp_f32_e32 v215, v214
	v_rcp_f32_e32 v161, v161
	v_add_f32_e32 v213, 1.0, v213
	v_rcp_f32_e32 v214, v213
	v_add_f32_e32 v213, 1.0, v215
	v_rcp_f32_e32 v215, v213
	v_pk_fma_f32 v[160:161], v[200:201], v[160:161], v[200:201] neg_lo:[1,0,0] neg_hi:[1,0,0]
	v_lshlrev_b32_e32 v200, 16, v162
	v_pk_mul_f32 v[154:155], v[154:155], v[160:161]
	v_and_b32_e32 v201, 0xffff0000, v162
	v_cvt_pk_bf16_f32 v160, v154, v155
	v_pk_fma_f32 v[154:155], v[202:203], v[214:215], v[202:203] neg_lo:[1,0,0] neg_hi:[1,0,0]
	v_mov_b64_e32 v[202:203], s[14:15]
	v_pk_mul_f32 v[154:155], v[156:157], v[154:155]
	v_lshlrev_b32_e32 v156, 16, v166
	v_cvt_pk_bf16_f32 v161, v154, v155
	v_lshlrev_b32_e32 v154, 16, v170
	v_and_b32_e32 v155, 0xffff0000, v170
	v_and_b32_e32 v157, 0xffff0000, v166
	v_pk_fma_f32 v[154:155], v[118:119], v[154:155], v[122:123]
	v_or_b32_e32 v162, 48, v212
	v_pk_fma_f32 v[154:155], v[126:127], v[156:157], v[154:155]
	s_nop 0
	v_pk_fma_f32 v[154:155], v[130:131], v[200:201], v[154:155]
	v_mad_i64_i32 v[200:201], s[0:1], v212, s60, v[202:203]
	v_mul_f32_e32 v156, v154, v154
	v_mul_f32_e32 v157, v155, v155
	v_fmaak_f32 v156, v252, v156, 0x40135761
	v_fmaak_f32 v157, v252, v157, 0x40135761
	v_mul_f32_e32 v156, v154, v156
	v_mul_f32_e32 v157, v155, v157
	v_exp_f32_e32 v156, v156
	v_exp_f32_e32 v157, v157
	v_lshl_add_u64 v[200:201], v[200:201], 0, v[198:199]
	global_store_dwordx4 v[200:201], v[158:161], off
	v_add_f32_e32 v156, 1.0, v156
	v_add_f32_e32 v157, 1.0, v157
	v_rcp_f32_e32 v156, v156
	v_rcp_f32_e32 v157, v157
	v_lshlrev_b32_e32 v158, 16, v163
	v_and_b32_e32 v159, 0xffff0000, v163
	v_or_b32_e32 v163, 32, v212
	v_pk_fma_f32 v[154:155], v[154:155], v[156:157], v[154:155] neg_lo:[1,0,0] neg_hi:[1,0,0]
	v_lshlrev_b32_e32 v156, 16, v167
	v_pk_mul_f32 v[150:151], v[150:151], v[154:155]
	v_lshlrev_b32_e32 v154, 16, v171
	v_and_b32_e32 v155, 0xffff0000, v171
	v_and_b32_e32 v157, 0xffff0000, v167
	v_pk_fma_f32 v[154:155], v[120:121], v[154:155], v[124:125]
	v_cvt_pk_bf16_f32 v150, v150, v151
	v_pk_fma_f32 v[154:155], v[128:129], v[156:157], v[154:155]
	s_nop 0
	v_pk_fma_f32 v[154:155], v[132:133], v[158:159], v[154:155]
	v_mad_i64_i32 v[158:159], s[0:1], v163, s60, v[204:205]
	v_add_co_u32_e32 v160, vcc, s61, v158
	v_mul_f32_e32 v156, v154, v154
	s_nop 0
	v_addc_co_u32_e32 v161, vcc, -1, v159, vcc
	global_load_dwordx4 v[214:217], v[158:159], off
	global_load_dwordx4 v[218:221], v[160:161], off offset:-3072
	v_add_co_u32_e32 v158, vcc, s62, v158
	v_fmaak_f32 v156, v252, v156, 0x40135761
	s_nop 0
	v_addc_co_u32_e32 v159, vcc, -1, v159, vcc
	global_load_dwordx4 v[222:225], v[158:159], off offset:-2048
	v_mul_f32_e32 v157, v155, v155
	v_mul_f32_e32 v156, v154, v156
	v_fmaak_f32 v157, v252, v157, 0x40135761
	v_mul_f32_e32 v157, v155, v157
	v_exp_f32_e32 v156, v156
	v_exp_f32_e32 v157, v157
	v_lshlrev_b32_e32 v158, 16, v164
	v_add_f32_e32 v151, 1.0, v156
	v_rcp_f32_e32 v156, v151
	v_add_f32_e32 v151, 1.0, v157
	v_rcp_f32_e32 v157, v151
	v_and_b32_e32 v159, 0xffff0000, v164
	v_lshlrev_b32_e32 v160, 16, v165
	v_and_b32_e32 v161, 0xffff0000, v165
	v_pk_fma_f32 v[154:155], v[154:155], v[156:157], v[154:155] neg_lo:[1,0,0] neg_hi:[1,0,0]
	v_lshlrev_b32_e32 v156, 16, v168
	v_pk_mul_f32 v[152:153], v[152:153], v[154:155]
	v_lshlrev_b32_e32 v154, 16, v172
	v_and_b32_e32 v155, 0xffff0000, v172
	v_and_b32_e32 v157, 0xffff0000, v168
	v_pk_fma_f32 v[154:155], v[102:103], v[154:155], v[114:115]
	s_waitcnt vmcnt(2)
	v_lshlrev_b32_e32 v166, 16, v215
	v_pk_fma_f32 v[154:155], v[106:107], v[156:157], v[154:155]
	v_and_b32_e32 v167, 0xffff0000, v215
	v_pk_fma_f32 v[154:155], v[110:111], v[158:159], v[154:155]
	v_lshlrev_b32_e32 v158, 16, v169
	v_mul_f32_e32 v151, v154, v154
	v_fmaak_f32 v151, v252, v151, 0x40135761
	v_mul_f32_e32 v151, v154, v151
	v_exp_f32_e32 v156, v151
	v_mul_f32_e32 v151, v155, v155
	v_fmaak_f32 v151, v252, v151, 0x40135761
	v_mul_f32_e32 v151, v155, v151
	v_exp_f32_e32 v157, v151
	v_cvt_pk_bf16_f32 v151, v152, v153
	v_add_f32_e32 v152, 1.0, v156
	v_lshlrev_b32_e32 v156, 16, v173
	v_add_f32_e32 v153, 1.0, v157
	v_and_b32_e32 v157, 0xffff0000, v173
	v_and_b32_e32 v159, 0xffff0000, v169
	v_pk_fma_f32 v[156:157], v[104:105], v[156:157], v[116:117]
	v_rcp_f32_e32 v152, v152
	v_pk_fma_f32 v[156:157], v[108:109], v[158:159], v[156:157]
	v_rcp_f32_e32 v153, v153
	v_pk_fma_f32 v[156:157], v[112:113], v[160:161], v[156:157]
	s_waitcnt vmcnt(1)
	v_lshlrev_b32_e32 v168, 16, v219
	v_mul_f32_e32 v158, v156, v156
	v_mul_f32_e32 v159, v157, v157
	v_fmaak_f32 v158, v252, v158, 0x40135761
	v_fmaak_f32 v159, v252, v159, 0x40135761
	v_mul_f32_e32 v158, v156, v158
	v_mul_f32_e32 v159, v157, v159
	v_exp_f32_e32 v158, v158
	v_exp_f32_e32 v159, v159
	v_pk_fma_f32 v[152:153], v[154:155], v[152:153], v[154:155] neg_lo:[1,0,0] neg_hi:[1,0,0]
	v_lshlrev_b32_e32 v154, 16, v214
	v_add_f32_e32 v158, 1.0, v158
	v_add_f32_e32 v159, 1.0, v159
	v_rcp_f32_e32 v158, v158
	v_rcp_f32_e32 v159, v159
	v_pk_mul_f32 v[146:147], v[146:147], v[152:153]
	v_and_b32_e32 v155, 0xffff0000, v214
	v_cvt_pk_bf16_f32 v152, v146, v147
	v_pk_fma_f32 v[146:147], v[156:157], v[158:159], v[156:157] neg_lo:[1,0,0] neg_hi:[1,0,0]
	v_lshlrev_b32_e32 v156, 16, v218
	v_and_b32_e32 v157, 0xffff0000, v218
	v_pk_fma_f32 v[154:155], v[118:119], v[154:155], v[122:123]
	s_waitcnt vmcnt(0)
; DI float bflo(unsigned w) { return __uint_as_float(w << 16); }
; DI float bfhi(unsigned w) { return __uint_as_float(w & 0xffff0000u); }
; DI u32x4 pack8(const f32x4& v0, const f32x4& v1) { u32x4 w; w.x = cvt_pk_bf16(v0[0], v0[1]); w.y = cvt_pk_bf16(v0[2], v0[3]); w.z = cvt_pk_bf16(v1[0], v1[1]); w.w = cvt_pk_bf16(v1[2], v1[3]); return w; }
; DI float gelu_tanh(float v) {
;     const float uu = 0.7978845608028654f * (v + 0.044715f * v * v * v);
;     const float e = __builtin_amdgcn_exp2f(2.8853900817779268f * uu);
;     return v - v * __builtin_amdgcn_rcpf(e + 1.0f);
;     DI void operator()(const AccT& acc, const Unit& u, int wr, int wc, int fr, int fq) const {
;     ...
;                     const int row = rowbase + ai * 128 + m * 16; const int sq = row & (SEQ - 1);
;                     const bf16_t* pa = A + (size_t)row * FF + col;
;                     a0[m] = *(const u32x4*)pa;
;                     a1[m] = *(const u32x4*)(pa - (sq >= 1 ? FF : 0));
;                     a2[m] = *(const u32x4*)(pa - (sq >= 2 ? 2 * FF : 0));
;                 }
; #pragma unroll
;                 for (int m = mb; m < mb + 2; ++m) {
;                     const int row = rowbase + ai * 128 + m * 16; const int sq = row & (SEQ - 1);
;                     const float k1 = sq >= 1 ? 1.0f : 0.0f, k2 = sq >= 2 ? 1.0f : 0.0f;
;                     const u32x4 x0 = a0[m], x1 = a1[m], x2 = a2[m];
;                     const float f0[8] = {bflo(x0.x), bfhi(x0.x), bflo(x0.y), bfhi(x0.y), bflo(x0.z), bfhi(x0.z), bflo(x0.w), bfhi(x0.w)};
;                     const float f1[8] = {bflo(x1.x), bfhi(x1.x), bflo(x1.y), bfhi(x1.y), bflo(x1.z), bfhi(x1.z), bflo(x1.w), bfhi(x1.w)};
;                     const float f2[8] = {bflo(x2.x), bfhi(x2.x), bflo(x2.y), bfhi(x2.y), bflo(x2.z), bfhi(x2.z), bflo(x2.w), bfhi(x2.w)};
;                     f32x4 o0, o1;
; #pragma unroll
;                     for (int j = 0; j < 4; ++j) {
;                         const float c0 = cb[0][j] + w0[0][j] * f0[j] + k1 * (w1[0][j] * f1[j]) + k2 * (w2[0][j] * f2[j]);
;                         const float c1 = cb[1][j] + w0[1][j] * f0[4 + j] + k1 * (w1[1][j] * f1[4 + j]) + k2 * (w2[1][j] * f2[4 + j]);
;                         o0[j] = gelu_tanh(c0) * acc[ai][bj][m][0][j]; o1[j] = gelu_tanh(c1) * acc[ai][bj][m][1][j];
;                     }
;                     *(u32x4*)(ACT + (size_t)row * FF + col) = pack8(o0, o1);
	v_lshlrev_b32_e32 v158, 16, v222
	v_and_b32_e32 v159, 0xffff0000, v222
	v_pk_fma_f32 v[154:155], v[126:127], v[156:157], v[154:155]
	v_pk_mul_f32 v[146:147], v[148:149], v[146:147]
	v_pk_fma_f32 v[158:159], v[130:131], v[158:159], v[154:155]
	v_cvt_pk_bf16_f32 v153, v146, v147
	v_mul_f32_e32 v154, v158, v158
	v_fmaak_f32 v154, v252, v154, 0x40135761
	v_mul_f32_e32 v154, v158, v154
	v_mad_i64_i32 v[146:147], s[0:1], v193, s60, v[202:203]
	v_lshl_add_u64 v[160:161], v[146:147], 0, v[198:199]
	global_store_dwordx4 v[160:161], v[150:153], off
	v_exp_f32_e32 v164, v154
	v_mul_f32_e32 v154, v159, v159
	v_mad_i64_i32 v[150:151], s[0:1], v162, s60, v[204:205]
	v_add_co_u32_e32 v152, vcc, s61, v150
	v_fmaak_f32 v154, v252, v154, 0x40135761
	s_nop 0
	v_addc_co_u32_e32 v153, vcc, -1, v151, vcc
	v_mul_f32_e32 v154, v159, v154
	global_load_dwordx4 v[146:149], v[150:151], off
	v_add_co_u32_e32 v150, vcc, s62, v150
	s_nop 0
	v_addc_co_u32_e32 v151, vcc, -1, v151, vcc
	v_exp_f32_e32 v165, v154
	global_load_dwordx4 v[154:157], v[152:153], off offset:-3072
	s_nop 0
	global_load_dwordx4 v[150:153], v[150:151], off offset:-2048
	v_and_b32_e32 v169, 0xffff0000, v219
	v_pk_fma_f32 v[166:167], v[120:121], v[166:167], v[124:125]
	v_lshlrev_b32_e32 v170, 16, v223
	v_and_b32_e32 v171, 0xffff0000, v223
	v_pk_fma_f32 v[166:167], v[128:129], v[168:169], v[166:167]
	v_add_f32_e32 v164, 1.0, v164
	v_pk_fma_f32 v[166:167], v[132:133], v[170:171], v[166:167]
	v_add_f32_e32 v165, 1.0, v165
	v_mul_f32_e32 v168, v166, v166
	v_mul_f32_e32 v169, v167, v167
	v_fmaak_f32 v168, v252, v168, 0x40135761
	v_fmaak_f32 v169, v252, v169, 0x40135761
	v_mul_f32_e32 v168, v166, v168
	v_mul_f32_e32 v169, v167, v169
	v_exp_f32_e32 v168, v168
	v_exp_f32_e32 v169, v169
	v_rcp_f32_e32 v164, v164
	v_rcp_f32_e32 v165, v165
	v_add_f32_e32 v168, 1.0, v168
	v_add_f32_e32 v169, 1.0, v169
	v_rcp_f32_e32 v168, v168
	v_rcp_f32_e32 v169, v169
	v_pk_fma_f32 v[158:159], v[158:159], v[164:165], v[158:159] neg_lo:[1,0,0] neg_hi:[1,0,0]
	v_lshlrev_b32_e32 v164, 16, v220
	v_pk_mul_f32 v[142:143], v[142:143], v[158:159]
	v_pk_fma_f32 v[158:159], v[166:167], v[168:169], v[166:167] neg_lo:[1,0,0] neg_hi:[1,0,0]
	v_and_b32_e32 v165, 0xffff0000, v220
	v_pk_mul_f32 v[144:145], v[144:145], v[158:159]
	v_lshlrev_b32_e32 v158, 16, v216
	v_and_b32_e32 v159, 0xffff0000, v216
	v_pk_fma_f32 v[158:159], v[102:103], v[158:159], v[114:115]
	v_lshlrev_b32_e32 v166, 16, v224
	v_and_b32_e32 v167, 0xffff0000, v224
	v_pk_fma_f32 v[158:159], v[106:107], v[164:165], v[158:159]
	v_cvt_pk_bf16_f32 v142, v142, v143
	v_pk_fma_f32 v[158:159], v[110:111], v[166:167], v[158:159]
	v_lshlrev_b32_e32 v166, 16, v221
	v_mul_f32_e32 v143, v158, v158
	v_fmaak_f32 v143, v252, v143, 0x40135761
	v_mul_f32_e32 v143, v158, v143
	v_exp_f32_e32 v164, v143
	v_mul_f32_e32 v143, v159, v159
	v_fmaak_f32 v143, v252, v143, 0x40135761
	v_mul_f32_e32 v143, v159, v143
	v_exp_f32_e32 v165, v143
	v_cvt_pk_bf16_f32 v143, v144, v145
	v_add_f32_e32 v144, 1.0, v164
	v_lshlrev_b32_e32 v164, 16, v217
	v_add_f32_e32 v145, 1.0, v165
	v_and_b32_e32 v165, 0xffff0000, v217
	v_and_b32_e32 v167, 0xffff0000, v221
	v_pk_fma_f32 v[164:165], v[104:105], v[164:165], v[116:117]
	v_lshlrev_b32_e32 v168, 16, v225
	v_and_b32_e32 v169, 0xffff0000, v225
	v_pk_fma_f32 v[164:165], v[108:109], v[166:167], v[164:165]
	v_rcp_f32_e32 v144, v144
	v_pk_fma_f32 v[164:165], v[112:113], v[168:169], v[164:165]
	v_rcp_f32_e32 v145, v145
	v_mul_f32_e32 v166, v164, v164
	v_mul_f32_e32 v167, v165, v165
	v_fmaak_f32 v166, v252, v166, 0x40135761
	v_fmaak_f32 v167, v252, v167, 0x40135761
	v_mul_f32_e32 v166, v164, v166
	v_mul_f32_e32 v167, v165, v167
	v_exp_f32_e32 v166, v166
	v_exp_f32_e32 v167, v167
	v_pk_fma_f32 v[144:145], v[158:159], v[144:145], v[158:159] neg_lo:[1,0,0] neg_hi:[1,0,0]
	v_add_f32_e32 v166, 1.0, v166
	v_add_f32_e32 v167, 1.0, v167
	v_rcp_f32_e32 v166, v166
	v_rcp_f32_e32 v167, v167
	v_pk_mul_f32 v[138:139], v[138:139], v[144:145]
	s_nop 0
	v_cvt_pk_bf16_f32 v144, v138, v139
	v_pk_fma_f32 v[138:139], v[164:165], v[166:167], v[164:165] neg_lo:[1,0,0] neg_hi:[1,0,0]
	s_waitcnt vmcnt(0)
	v_lshlrev_b32_e32 v164, 16, v150
	v_pk_mul_f32 v[138:139], v[140:141], v[138:139]
	v_lshlrev_b32_e32 v140, 16, v154
	v_cvt_pk_bf16_f32 v145, v138, v139
	v_mad_i64_i32 v[138:139], s[0:1], v163, s60, v[202:203]
	v_lshl_add_u64 v[158:159], v[138:139], 0, v[198:199]
	v_lshlrev_b32_e32 v138, 16, v146
	v_and_b32_e32 v139, 0xffff0000, v146
	v_and_b32_e32 v141, 0xffff0000, v154
	v_pk_fma_f32 v[138:139], v[118:119], v[138:139], v[122:123]
	global_store_dwordx4 v[158:159], v[142:145], off
	v_and_b32_e32 v165, 0xffff0000, v150
	v_pk_fma_f32 v[138:139], v[126:127], v[140:141], v[138:139]
	v_lshlrev_b32_e32 v142, 16, v147
	v_and_b32_e32 v143, 0xffff0000, v147
	v_lshlrev_b32_e32 v144, 16, v155
	v_and_b32_e32 v145, 0xffff0000, v155
	v_pk_fma_f32 v[142:143], v[120:121], v[142:143], v[124:125]
	v_pk_fma_f32 v[138:139], v[130:131], v[164:165], v[138:139]
	v_lshlrev_b32_e32 v146, 16, v151
	v_and_b32_e32 v147, 0xffff0000, v151
	v_pk_fma_f32 v[142:143], v[128:129], v[144:145], v[142:143]
	v_mul_f32_e32 v140, v138, v138
	v_mul_f32_e32 v141, v139, v139
	v_pk_fma_f32 v[142:143], v[132:133], v[146:147], v[142:143]
	v_fmaak_f32 v140, v252, v140, 0x40135761
	v_fmaak_f32 v141, v252, v141, 0x40135761
	v_mul_f32_e32 v144, v142, v142
	v_mul_f32_e32 v145, v143, v143
	v_mul_f32_e32 v140, v138, v140
	v_mul_f32_e32 v141, v139, v141
	v_fmaak_f32 v144, v252, v144, 0x40135761
	v_fmaak_f32 v145, v252, v145, 0x40135761
	v_mul_f32_e32 v144, v142, v144
	v_mul_f32_e32 v145, v143, v145
	v_exp_f32_e32 v140, v140
	v_exp_f32_e32 v141, v141
; DI float bflo(unsigned w) { return __uint_as_float(w << 16); }
; DI float bfhi(unsigned w) { return __uint_as_float(w & 0xffff0000u); }
; DI float gelu_tanh(float v) {
;     const float uu = 0.7978845608028654f * (v + 0.044715f * v * v * v);
;     const float e = __builtin_amdgcn_exp2f(2.8853900817779268f * uu);
;     return v - v * __builtin_amdgcn_rcpf(e + 1.0f);
;     DI void operator()(const AccT& acc, const Unit& u, int wr, int wc, int fr, int fq) const {
;     ...
;             for (int aim = 0; aim < 4; ++aim) { const int ai = aim >> 1, mb = (aim & 1) * 2;
;                 u32x4 a0[4], a1[4], a2[4];
; #pragma unroll
;                 for (int m = mb; m < mb + 2; ++m) {
;                     const int row = rowbase + ai * 128 + m * 16; const int sq = row & (SEQ - 1);
;                     const bf16_t* pa = A + (size_t)row * FF + col;
;                     a0[m] = *(const u32x4*)pa;
;                     a1[m] = *(const u32x4*)(pa - (sq >= 1 ? FF : 0));
;                     a2[m] = *(const u32x4*)(pa - (sq >= 2 ? 2 * FF : 0));
;                 }
; #pragma unroll
;                 for (int m = mb; m < mb + 2; ++m) {
;                     const int row = rowbase + ai * 128 + m * 16; const int sq = row & (SEQ - 1);
;                     const float k1 = sq >= 1 ? 1.0f : 0.0f, k2 = sq >= 2 ? 1.0f : 0.0f;
;                     const u32x4 x0 = a0[m], x1 = a1[m], x2 = a2[m];
;                     const float f0[8] = {bflo(x0.x), bfhi(x0.x), bflo(x0.y), bfhi(x0.y), bflo(x0.z), bfhi(x0.z), bflo(x0.w), bfhi(x0.w)};
;                     const float f1[8] = {bflo(x1.x), bfhi(x1.x), bflo(x1.y), bfhi(x1.y), bflo(x1.z), bfhi(x1.z), bflo(x1.w), bfhi(x1.w)};
;                     const float f2[8] = {bflo(x2.x), bfhi(x2.x), bflo(x2.y), bfhi(x2.y), bflo(x2.z), bfhi(x2.z), bflo(x2.w), bfhi(x2.w)};
;                     f32x4 o0, o1;
; #pragma unroll
;                     for (int j = 0; j < 4; ++j) {
;                         const float c0 = cb[0][j] + w0[0][j] * f0[j] + k1 * (w1[0][j] * f1[j]) + k2 * (w2[0][j] * f2[j]);
;                         const float c1 = cb[1][j] + w0[1][j] * f0[4 + j] + k1 * (w1[1][j] * f1[4 + j]) + k2 * (w2[1][j] * f2[4 + j]);
;                         o0[j] = gelu_tanh(c0) * acc[ai][bj][m][0][j]; o1[j] = gelu_tanh(c1) * acc[ai][bj][m][1][j];
;                     }
;                     *(u32x4*)(ACT + (size_t)row * FF + col) = pack8(o0, o1);
	v_exp_f32_e32 v144, v144
	v_exp_f32_e32 v145, v145
	v_add_f32_e32 v140, 1.0, v140
	v_add_f32_e32 v141, 1.0, v141
	v_rcp_f32_e32 v140, v140
	v_rcp_f32_e32 v141, v141
	v_add_f32_e32 v144, 1.0, v144
	v_add_f32_e32 v145, 1.0, v145
	v_rcp_f32_e32 v144, v144
	v_rcp_f32_e32 v145, v145
	v_pk_fma_f32 v[138:139], v[138:139], v[140:141], v[138:139] neg_lo:[1,0,0] neg_hi:[1,0,0]
	s_nop 0
	v_pk_mul_f32 v[134:135], v[134:135], v[138:139]
	v_pk_fma_f32 v[138:139], v[142:143], v[144:145], v[142:143] neg_lo:[1,0,0] neg_hi:[1,0,0]
	v_add_u32_e32 v143, 0x80, v212
	v_cvt_pk_bf16_f32 v134, v134, v135
	v_pk_mul_f32 v[136:137], v[136:137], v[138:139]
	v_and_b32_e32 v135, 0x1fcf, v143
	v_mad_i64_i32 v[138:139], s[0:1], v143, s60, v[204:205]
	v_cmp_eq_u32_e32 vcc, 0, v135
	v_cmp_lt_u32_e64 s[0:1], 1, v135
	v_lshlrev_b32_e32 v144, 16, v152
	v_cndmask_b32_e64 v147, -1, 0, vcc
	v_cndmask_b32_e64 v146, v210, 0, vcc
	v_cndmask_b32_e64 v151, 0, -1, s[0:1]
	v_cndmask_b32_e64 v150, 0, v211, s[0:1]
	v_lshl_add_u64 v[140:141], v[138:139], 0, v[146:147]
	global_load_dwordx4 v[164:167], v[138:139], off
	global_load_dwordx4 v[168:171], v[140:141], off
	v_lshl_add_u64 v[138:139], v[138:139], 0, v[150:151]
	global_load_dwordx4 v[214:217], v[138:139], off
	v_lshlrev_b32_e32 v138, 16, v148
	v_and_b32_e32 v139, 0xffff0000, v148
	v_lshlrev_b32_e32 v140, 16, v156
	v_and_b32_e32 v141, 0xffff0000, v156
	v_pk_fma_f32 v[138:139], v[102:103], v[138:139], v[114:115]
	v_and_b32_e32 v145, 0xffff0000, v152
	v_pk_fma_f32 v[138:139], v[106:107], v[140:141], v[138:139]
	v_lshlrev_b32_e32 v148, 16, v153
	v_pk_fma_f32 v[138:139], v[110:111], v[144:145], v[138:139]
	v_lshlrev_b32_e32 v144, 16, v157
	v_mul_f32_e32 v135, v138, v138
	v_fmaak_f32 v135, v252, v135, 0x40135761
	v_mul_f32_e32 v135, v138, v135
	v_exp_f32_e32 v140, v135
	v_mul_f32_e32 v135, v139, v139
	v_fmaak_f32 v135, v252, v135, 0x40135761
	v_mul_f32_e32 v135, v139, v135
	v_exp_f32_e32 v141, v135
	v_cvt_pk_bf16_f32 v135, v136, v137
	v_add_f32_e32 v136, 1.0, v140
	v_lshlrev_b32_e32 v140, 16, v149
	v_add_f32_e32 v137, 1.0, v141
	v_and_b32_e32 v141, 0xffff0000, v149
	v_and_b32_e32 v145, 0xffff0000, v157
	v_pk_fma_f32 v[140:141], v[104:105], v[140:141], v[116:117]
	v_and_b32_e32 v149, 0xffff0000, v153
	v_pk_fma_f32 v[140:141], v[108:109], v[144:145], v[140:141]
	v_rcp_f32_e32 v136, v136
	v_pk_fma_f32 v[140:141], v[112:113], v[148:149], v[140:141]
	v_rcp_f32_e32 v137, v137
	v_mul_f32_e32 v142, v140, v140
	v_fmaak_f32 v142, v252, v142, 0x40135761
	v_mul_f32_e32 v144, v141, v141
	v_mul_f32_e32 v142, v140, v142
	v_fmaak_f32 v144, v252, v144, 0x40135761
	v_mul_f32_e32 v144, v141, v144
	v_exp_f32_e32 v142, v142
	v_exp_f32_e32 v145, v144
	v_pk_fma_f32 v[136:137], v[138:139], v[136:137], v[138:139] neg_lo:[1,0,0] neg_hi:[1,0,0]
	v_add_f32_e32 v142, 1.0, v142
	v_rcp_f32_e32 v144, v142
	v_add_f32_e32 v142, 1.0, v145
	v_rcp_f32_e32 v145, v142
	v_pk_mul_f32 v[98:99], v[98:99], v[136:137]
	v_cndmask_b32_e64 v142, 0, 1.0, s[0:1]
	v_cvt_pk_bf16_f32 v136, v98, v99
	v_pk_fma_f32 v[98:99], v[140:141], v[144:145], v[140:141] neg_lo:[1,0,0] neg_hi:[1,0,0]
	v_add_u32_e32 v145, 0x90, v212
	v_cndmask_b32_e64 v144, 1.0, 0, vcc
	v_pk_mul_f32 v[98:99], v[100:101], v[98:99]
	s_waitcnt vmcnt(2)
	v_lshlrev_b32_e32 v138, 16, v164
	v_and_b32_e32 v139, 0xffff0000, v164
	s_waitcnt vmcnt(1)
	v_lshlrev_b32_e32 v140, 16, v168
	v_and_b32_e32 v141, 0xffff0000, v168
	s_waitcnt vmcnt(0)
	v_lshlrev_b32_e32 v152, 16, v214
	v_and_b32_e32 v153, 0xffff0000, v214
	v_pk_fma_f32 v[138:139], v[118:119], v[138:139], v[122:123]
	v_pk_mul_f32 v[140:141], v[126:127], v[140:141]
	v_cvt_pk_bf16_f32 v137, v98, v99
	v_pk_fma_f32 v[138:139], v[144:145], v[140:141], v[138:139] op_sel_hi:[0,1,1]
	v_pk_mul_f32 v[140:141], v[130:131], v[152:153]
	v_mad_i64_i32 v[98:99], s[4:5], v162, s60, v[202:203]
	v_pk_fma_f32 v[152:153], v[142:143], v[140:141], v[138:139] op_sel_hi:[0,1,1]
	v_mul_f32_e32 v138, v152, v152
	v_fmaak_f32 v138, v252, v138, 0x40135761
	v_mul_f32_e32 v138, v152, v138
	v_lshl_add_u64 v[148:149], v[98:99], 0, v[198:199]
	global_store_dwordx4 v[148:149], v[134:137], off
	v_exp_f32_e32 v154, v138
	v_mul_f32_e32 v138, v153, v153
	v_mad_i64_i32 v[134:135], s[4:5], v145, s60, v[204:205]
	v_add_co_u32_e64 v136, s[4:5], s61, v134
	v_fmaak_f32 v138, v252, v138, 0x40135761
	s_nop 0
	v_addc_co_u32_e64 v137, s[4:5], -1, v135, s[4:5]
	v_mul_f32_e32 v138, v153, v138
	global_load_dwordx4 v[98:101], v[134:135], off
	v_add_co_u32_e64 v134, s[4:5], s62, v134
	s_nop 0
	v_addc_co_u32_e64 v135, s[4:5], -1, v135, s[4:5]
	v_exp_f32_e32 v155, v138
	global_load_dwordx4 v[138:141], v[136:137], off offset:-3072
	s_nop 0
	global_load_dwordx4 v[134:137], v[134:135], off offset:-2048
	v_lshlrev_b32_e32 v156, 16, v165
	v_and_b32_e32 v157, 0xffff0000, v165
	v_lshlrev_b32_e32 v164, 16, v169
	v_and_b32_e32 v165, 0xffff0000, v169
	v_lshlrev_b32_e32 v168, 16, v215
	v_and_b32_e32 v169, 0xffff0000, v215
	v_pk_fma_f32 v[156:157], v[120:121], v[156:157], v[124:125]
	v_pk_mul_f32 v[164:165], v[128:129], v[164:165]
	v_add_f32_e32 v154, 1.0, v154
	v_pk_fma_f32 v[156:157], v[144:145], v[164:165], v[156:157] op_sel_hi:[0,1,1]
	v_pk_mul_f32 v[164:165], v[132:133], v[168:169]
	v_add_f32_e32 v155, 1.0, v155
	v_pk_fma_f32 v[156:157], v[142:143], v[164:165], v[156:157] op_sel_hi:[0,1,1]
	v_mul_f32_e32 v164, v156, v156
	v_mul_f32_e32 v165, v157, v157
	v_fmaak_f32 v164, v252, v164, 0x40135761
	v_fmaak_f32 v165, v252, v165, 0x40135761
	v_mul_f32_e32 v164, v156, v164
	v_mul_f32_e32 v165, v157, v165
	v_exp_f32_e32 v164, v164
	v_exp_f32_e32 v165, v165
	v_rcp_f32_e32 v154, v154
	v_rcp_f32_e32 v155, v155
	v_add_f32_e32 v164, 1.0, v164
; DI float bflo(unsigned w) { return __uint_as_float(w << 16); }
; DI float bfhi(unsigned w) { return __uint_as_float(w & 0xffff0000u); }
; DI float gelu_tanh(float v) {
;     const float uu = 0.7978845608028654f * (v + 0.044715f * v * v * v);
;     const float e = __builtin_amdgcn_exp2f(2.8853900817779268f * uu);
;     return v - v * __builtin_amdgcn_rcpf(e + 1.0f);
;     DI void operator()(const AccT& acc, const Unit& u, int wr, int wc, int fr, int fq) const {
;     ...
;             for (int aim = 0; aim < 4; ++aim) { const int ai = aim >> 1, mb = (aim & 1) * 2;
;                 u32x4 a0[4], a1[4], a2[4];
; #pragma unroll
;                 for (int m = mb; m < mb + 2; ++m) {
;                     const int row = rowbase + ai * 128 + m * 16; const int sq = row & (SEQ - 1);
;                     const bf16_t* pa = A + (size_t)row * FF + col;
;                     a0[m] = *(const u32x4*)pa;
;                     a1[m] = *(const u32x4*)(pa - (sq >= 1 ? FF : 0));
;                     a2[m] = *(const u32x4*)(pa - (sq >= 2 ? 2 * FF : 0));
;                 }
; #pragma unroll
;                 for (int m = mb; m < mb + 2; ++m) {
;                     const int row = rowbase + ai * 128 + m * 16; const int sq = row & (SEQ - 1);
;                     const float k1 = sq >= 1 ? 1.0f : 0.0f, k2 = sq >= 2 ? 1.0f : 0.0f;
;                     const u32x4 x0 = a0[m], x1 = a1[m], x2 = a2[m];
;                     const float f0[8] = {bflo(x0.x), bfhi(x0.x), bflo(x0.y), bfhi(x0.y), bflo(x0.z), bfhi(x0.z), bflo(x0.w), bfhi(x0.w)};
;                     const float f1[8] = {bflo(x1.x), bfhi(x1.x), bflo(x1.y), bfhi(x1.y), bflo(x1.z), bfhi(x1.z), bflo(x1.w), bfhi(x1.w)};
;                     const float f2[8] = {bflo(x2.x), bfhi(x2.x), bflo(x2.y), bfhi(x2.y), bflo(x2.z), bfhi(x2.z), bflo(x2.w), bfhi(x2.w)};
;                     f32x4 o0, o1;
; #pragma unroll
;                     for (int j = 0; j < 4; ++j) {
;                         const float c0 = cb[0][j] + w0[0][j] * f0[j] + k1 * (w1[0][j] * f1[j]) + k2 * (w2[0][j] * f2[j]);
;                         const float c1 = cb[1][j] + w0[1][j] * f0[4 + j] + k1 * (w1[1][j] * f1[4 + j]) + k2 * (w2[1][j] * f2[4 + j]);
;                         o0[j] = gelu_tanh(c0) * acc[ai][bj][m][0][j]; o1[j] = gelu_tanh(c1) * acc[ai][bj][m][1][j];
;                     }
;                     *(u32x4*)(ACT + (size_t)row * FF + col) = pack8(o0, o1);
	v_add_f32_e32 v165, 1.0, v165
	v_rcp_f32_e32 v164, v164
	v_rcp_f32_e32 v165, v165
	v_pk_fma_f32 v[152:153], v[152:153], v[154:155], v[152:153] neg_lo:[1,0,0] neg_hi:[1,0,0]
	v_lshlrev_b32_e32 v154, 16, v170
	v_pk_mul_f32 v[94:95], v[94:95], v[152:153]
	v_pk_fma_f32 v[152:153], v[156:157], v[164:165], v[156:157] neg_lo:[1,0,0] neg_hi:[1,0,0]
	v_and_b32_e32 v155, 0xffff0000, v170
	v_pk_mul_f32 v[96:97], v[96:97], v[152:153]
	v_lshlrev_b32_e32 v152, 16, v166
	v_and_b32_e32 v153, 0xffff0000, v166
	v_lshlrev_b32_e32 v156, 16, v216
	v_and_b32_e32 v157, 0xffff0000, v216
	v_pk_fma_f32 v[152:153], v[102:103], v[152:153], v[114:115]
	v_pk_mul_f32 v[154:155], v[106:107], v[154:155]
	v_cvt_pk_bf16_f32 v94, v94, v95
	v_pk_fma_f32 v[152:153], v[144:145], v[154:155], v[152:153] op_sel_hi:[0,1,1]
	v_pk_mul_f32 v[154:155], v[110:111], v[156:157]
	v_lshlrev_b32_e32 v156, 16, v171
	v_pk_fma_f32 v[152:153], v[142:143], v[154:155], v[152:153] op_sel_hi:[0,1,1]
	v_mul_f32_e32 v95, v152, v152
	v_fmaak_f32 v95, v252, v95, 0x40135761
	v_mul_f32_e32 v95, v152, v95
	v_exp_f32_e32 v154, v95
	v_mul_f32_e32 v95, v153, v153
	v_fmaak_f32 v95, v252, v95, 0x40135761
	v_mul_f32_e32 v95, v153, v95
	v_exp_f32_e32 v155, v95
	v_cvt_pk_bf16_f32 v95, v96, v97
	v_add_f32_e32 v96, 1.0, v154
	v_lshlrev_b32_e32 v154, 16, v167
	v_add_f32_e32 v97, 1.0, v155
	v_and_b32_e32 v155, 0xffff0000, v167
	v_and_b32_e32 v157, 0xffff0000, v171
	v_lshlrev_b32_e32 v164, 16, v217
	v_and_b32_e32 v165, 0xffff0000, v217
	v_pk_fma_f32 v[154:155], v[104:105], v[154:155], v[116:117]
	v_pk_mul_f32 v[156:157], v[108:109], v[156:157]
	v_rcp_f32_e32 v96, v96
	v_pk_fma_f32 v[154:155], v[144:145], v[156:157], v[154:155] op_sel_hi:[0,1,1]
	v_pk_mul_f32 v[156:157], v[112:113], v[164:165]
	v_rcp_f32_e32 v97, v97
	v_pk_fma_f32 v[154:155], v[142:143], v[156:157], v[154:155] op_sel_hi:[0,1,1]
	v_mul_f32_e32 v156, v154, v154
	v_mul_f32_e32 v157, v155, v155
	v_fmaak_f32 v156, v252, v156, 0x40135761
	v_fmaak_f32 v157, v252, v157, 0x40135761
	v_mul_f32_e32 v156, v154, v156
	v_mul_f32_e32 v157, v155, v157
	v_exp_f32_e32 v156, v156
	v_exp_f32_e32 v157, v157
	v_pk_fma_f32 v[96:97], v[152:153], v[96:97], v[152:153] neg_lo:[1,0,0] neg_hi:[1,0,0]
	s_waitcnt vmcnt(1)
	v_lshlrev_b32_e32 v152, 16, v138
	v_add_f32_e32 v156, 1.0, v156
	v_add_f32_e32 v157, 1.0, v157
	v_rcp_f32_e32 v156, v156
	v_rcp_f32_e32 v157, v157
	v_pk_mul_f32 v[90:91], v[90:91], v[96:97]
	v_and_b32_e32 v153, 0xffff0000, v138
	v_cvt_pk_bf16_f32 v96, v90, v91
	v_pk_fma_f32 v[90:91], v[154:155], v[156:157], v[154:155] neg_lo:[1,0,0] neg_hi:[1,0,0]
	s_waitcnt vmcnt(0)
	v_lshlrev_b32_e32 v154, 16, v134
	v_pk_mul_f32 v[90:91], v[92:93], v[90:91]
	v_lshlrev_b32_e32 v92, 16, v98
	v_and_b32_e32 v93, 0xffff0000, v98
	v_pk_fma_f32 v[92:93], v[118:119], v[92:93], v[122:123]
	v_and_b32_e32 v155, 0xffff0000, v134
	v_pk_fma_f32 v[92:93], v[126:127], v[152:153], v[92:93]
	v_mad_i64_i32 v[152:153], s[0:1], v143, s60, v[202:203]
	v_pk_fma_f32 v[92:93], v[130:131], v[154:155], v[92:93]
	v_lshl_add_u64 v[152:153], v[152:153], 0, v[198:199]
	v_mul_f32_e32 v97, v92, v92
	v_fmaak_f32 v97, v252, v97, 0x40135761
	v_mul_f32_e32 v97, v92, v97
	v_exp_f32_e32 v98, v97
	v_mul_f32_e32 v97, v93, v93
	v_fmaak_f32 v97, v252, v97, 0x40135761
	v_mul_f32_e32 v97, v93, v97
	v_exp_f32_e32 v134, v97
	v_cvt_pk_bf16_f32 v97, v90, v91
	v_add_f32_e32 v90, 1.0, v98
	v_rcp_f32_e32 v90, v90
	v_add_f32_e32 v91, 1.0, v134
	v_rcp_f32_e32 v91, v91
	global_store_dwordx4 v[152:153], v[94:97], off
	v_add_u32_e32 v138, 0xb0, v212
	v_pk_fma_f32 v[90:91], v[92:93], v[90:91], v[92:93] neg_lo:[1,0,0] neg_hi:[1,0,0]
	v_lshlrev_b32_e32 v92, 16, v139
	v_and_b32_e32 v93, 0xffff0000, v139
	v_add_u32_e32 v139, 0xa0, v212
	v_pk_mul_f32 v[86:87], v[86:87], v[90:91]
	v_lshlrev_b32_e32 v90, 16, v99
	v_and_b32_e32 v91, 0xffff0000, v99
	v_mad_i64_i32 v[98:99], s[0:1], v139, s60, v[204:205]
	v_pk_fma_f32 v[90:91], v[120:121], v[90:91], v[124:125]
	v_add_co_u32_e32 v134, vcc, s61, v98
	v_lshlrev_b32_e32 v94, 16, v135
	v_and_b32_e32 v95, 0xffff0000, v135
	v_pk_fma_f32 v[90:91], v[128:129], v[92:93], v[90:91]
	v_addc_co_u32_e32 v135, vcc, -1, v99, vcc
	v_pk_fma_f32 v[90:91], v[132:133], v[94:95], v[90:91]
	global_load_dwordx4 v[94:97], v[98:99], off
	global_load_dwordx4 v[154:157], v[134:135], off offset:-3072
	v_add_co_u32_e32 v98, vcc, s62, v98
	v_mul_f32_e32 v92, v90, v90
	s_nop 0
	v_addc_co_u32_e32 v99, vcc, -1, v99, vcc
	global_load_dwordx4 v[164:167], v[98:99], off offset:-2048
	v_fmaak_f32 v92, v252, v92, 0x40135761
	v_mul_f32_e32 v93, v91, v91
	v_mul_f32_e32 v92, v90, v92
	v_fmaak_f32 v93, v252, v93, 0x40135761
	v_mul_f32_e32 v93, v91, v93
	v_exp_f32_e32 v92, v92
	v_exp_f32_e32 v93, v93
	v_cvt_pk_bf16_f32 v86, v86, v87
	v_add_f32_e32 v87, 1.0, v92
	v_rcp_f32_e32 v92, v87
	v_add_f32_e32 v87, 1.0, v93
	v_rcp_f32_e32 v93, v87
	v_lshlrev_b32_e32 v98, 16, v136
	v_and_b32_e32 v99, 0xffff0000, v136
	v_pk_fma_f32 v[90:91], v[90:91], v[92:93], v[90:91] neg_lo:[1,0,0] neg_hi:[1,0,0]
	s_nop 0
	v_pk_mul_f32 v[88:89], v[88:89], v[90:91]
	v_lshlrev_b32_e32 v90, 16, v100
	v_and_b32_e32 v91, 0xffff0000, v100
	v_lshlrev_b32_e32 v92, 16, v140
	v_and_b32_e32 v93, 0xffff0000, v140
	v_pk_fma_f32 v[90:91], v[102:103], v[90:91], v[114:115]
	v_lshlrev_b32_e32 v100, 16, v137
	v_pk_fma_f32 v[90:91], v[106:107], v[92:93], v[90:91]
	s_waitcnt vmcnt(1)
; DI float bflo(unsigned w) { return __uint_as_float(w << 16); }
; DI float bfhi(unsigned w) { return __uint_as_float(w & 0xffff0000u); }
; DI u32x4 pack8(const f32x4& v0, const f32x4& v1) { u32x4 w; w.x = cvt_pk_bf16(v0[0], v0[1]); w.y = cvt_pk_bf16(v0[2], v0[3]); w.z = cvt_pk_bf16(v1[0], v1[1]); w.w = cvt_pk_bf16(v1[2], v1[3]); return w; }
; DI float gelu_tanh(float v) {
;     const float uu = 0.7978845608028654f * (v + 0.044715f * v * v * v);
;     const float e = __builtin_amdgcn_exp2f(2.8853900817779268f * uu);
;     return v - v * __builtin_amdgcn_rcpf(e + 1.0f);
;     DI void operator()(const AccT& acc, const Unit& u, int wr, int wc, int fr, int fq) const {
;     ...
;                     const int row = rowbase + ai * 128 + m * 16; const int sq = row & (SEQ - 1);
;                     const bf16_t* pa = A + (size_t)row * FF + col;
;                     a0[m] = *(const u32x4*)pa;
;                     a1[m] = *(const u32x4*)(pa - (sq >= 1 ? FF : 0));
;                     a2[m] = *(const u32x4*)(pa - (sq >= 2 ? 2 * FF : 0));
;                 }
; #pragma unroll
;                 for (int m = mb; m < mb + 2; ++m) {
;                     const int row = rowbase + ai * 128 + m * 16; const int sq = row & (SEQ - 1);
;                     const float k1 = sq >= 1 ? 1.0f : 0.0f, k2 = sq >= 2 ? 1.0f : 0.0f;
;                     const u32x4 x0 = a0[m], x1 = a1[m], x2 = a2[m];
;                     const float f0[8] = {bflo(x0.x), bfhi(x0.x), bflo(x0.y), bfhi(x0.y), bflo(x0.z), bfhi(x0.z), bflo(x0.w), bfhi(x0.w)};
;                     const float f1[8] = {bflo(x1.x), bfhi(x1.x), bflo(x1.y), bfhi(x1.y), bflo(x1.z), bfhi(x1.z), bflo(x1.w), bfhi(x1.w)};
;                     const float f2[8] = {bflo(x2.x), bfhi(x2.x), bflo(x2.y), bfhi(x2.y), bflo(x2.z), bfhi(x2.z), bflo(x2.w), bfhi(x2.w)};
;                     f32x4 o0, o1;
; #pragma unroll
;                     for (int j = 0; j < 4; ++j) {
;                         const float c0 = cb[0][j] + w0[0][j] * f0[j] + k1 * (w1[0][j] * f1[j]) + k2 * (w2[0][j] * f2[j]);
;                         const float c1 = cb[1][j] + w0[1][j] * f0[4 + j] + k1 * (w1[1][j] * f1[4 + j]) + k2 * (w2[1][j] * f2[4 + j]);
;                         o0[j] = gelu_tanh(c0) * acc[ai][bj][m][0][j]; o1[j] = gelu_tanh(c1) * acc[ai][bj][m][1][j];
;                     }
;                     *(u32x4*)(ACT + (size_t)row * FF + col) = pack8(o0, o1);
	v_lshlrev_b32_e32 v134, 16, v155
	v_pk_fma_f32 v[90:91], v[110:111], v[98:99], v[90:91]
	v_lshlrev_b32_e32 v98, 16, v141
	v_mul_f32_e32 v87, v90, v90
	v_fmaak_f32 v87, v252, v87, 0x40135761
	v_mul_f32_e32 v87, v90, v87
	v_exp_f32_e32 v92, v87
	v_mul_f32_e32 v87, v91, v91
	v_fmaak_f32 v87, v252, v87, 0x40135761
	v_mul_f32_e32 v87, v91, v87
	v_exp_f32_e32 v93, v87
	v_cvt_pk_bf16_f32 v87, v88, v89
	v_add_f32_e32 v88, 1.0, v92
	v_lshlrev_b32_e32 v92, 16, v101
	v_add_f32_e32 v89, 1.0, v93
	v_and_b32_e32 v93, 0xffff0000, v101
	v_and_b32_e32 v99, 0xffff0000, v141
	v_pk_fma_f32 v[92:93], v[104:105], v[92:93], v[116:117]
	v_and_b32_e32 v101, 0xffff0000, v137
	v_pk_fma_f32 v[92:93], v[108:109], v[98:99], v[92:93]
	v_rcp_f32_e32 v88, v88
	v_pk_fma_f32 v[92:93], v[112:113], v[100:101], v[92:93]
	v_rcp_f32_e32 v89, v89
	v_mul_f32_e32 v98, v92, v92
	v_mul_f32_e32 v99, v93, v93
	v_fmaak_f32 v98, v252, v98, 0x40135761
	v_fmaak_f32 v99, v252, v99, 0x40135761
	v_mul_f32_e32 v98, v92, v98
	v_mul_f32_e32 v99, v93, v99
	v_exp_f32_e32 v98, v98
	v_exp_f32_e32 v99, v99
	v_pk_fma_f32 v[88:89], v[90:91], v[88:89], v[90:91] neg_lo:[1,0,0] neg_hi:[1,0,0]
	v_lshlrev_b32_e32 v90, 16, v94
	v_add_f32_e32 v98, 1.0, v98
	v_add_f32_e32 v99, 1.0, v99
	v_rcp_f32_e32 v98, v98
	v_rcp_f32_e32 v99, v99
	v_pk_mul_f32 v[82:83], v[82:83], v[88:89]
	v_and_b32_e32 v91, 0xffff0000, v94
	v_cvt_pk_bf16_f32 v88, v82, v83
	v_pk_fma_f32 v[82:83], v[92:93], v[98:99], v[92:93] neg_lo:[1,0,0] neg_hi:[1,0,0]
	v_lshlrev_b32_e32 v92, 16, v154
	v_and_b32_e32 v93, 0xffff0000, v154
	v_pk_fma_f32 v[90:91], v[118:119], v[90:91], v[122:123]
	s_waitcnt vmcnt(0)
	v_lshlrev_b32_e32 v98, 16, v164
	v_and_b32_e32 v99, 0xffff0000, v164
	v_pk_fma_f32 v[90:91], v[126:127], v[92:93], v[90:91]
	v_pk_mul_f32 v[82:83], v[84:85], v[82:83]
	v_pk_fma_f32 v[98:99], v[130:131], v[98:99], v[90:91]
	v_cvt_pk_bf16_f32 v89, v82, v83
	v_mul_f32_e32 v90, v98, v98
	v_fmaak_f32 v90, v252, v90, 0x40135761
	v_mul_f32_e32 v90, v98, v90
	v_mad_i64_i32 v[82:83], s[0:1], v145, s60, v[202:203]
	v_lshl_add_u64 v[136:137], v[82:83], 0, v[198:199]
	global_store_dwordx4 v[136:137], v[86:89], off
	v_exp_f32_e32 v94, v90
	v_mul_f32_e32 v90, v99, v99
	v_mad_i64_i32 v[86:87], s[0:1], v138, s60, v[204:205]
	v_add_co_u32_e32 v88, vcc, s61, v86
	v_fmaak_f32 v90, v252, v90, 0x40135761
	s_nop 0
	v_addc_co_u32_e32 v89, vcc, -1, v87, vcc
	v_mul_f32_e32 v90, v99, v90
	global_load_dwordx4 v[82:85], v[86:87], off
	v_add_co_u32_e32 v86, vcc, s62, v86
	s_nop 0
	v_addc_co_u32_e32 v87, vcc, -1, v87, vcc
	v_exp_f32_e32 v100, v90
	global_load_dwordx4 v[90:93], v[88:89], off offset:-3072
	s_nop 0
	global_load_dwordx4 v[86:89], v[86:87], off offset:-2048
	v_and_b32_e32 v101, 0xffff0000, v95
	v_and_b32_e32 v135, 0xffff0000, v155
	v_add_f32_e32 v154, 1.0, v100
	v_lshlrev_b32_e32 v100, 16, v95
	v_pk_fma_f32 v[100:101], v[120:121], v[100:101], v[124:125]
	v_lshlrev_b32_e32 v140, 16, v165
	v_and_b32_e32 v141, 0xffff0000, v165
	v_pk_fma_f32 v[100:101], v[128:129], v[134:135], v[100:101]
	v_add_f32_e32 v94, 1.0, v94
	v_pk_fma_f32 v[100:101], v[132:133], v[140:141], v[100:101]
	v_rcp_f32_e32 v94, v94
	v_mul_f32_e32 v95, v100, v100
	v_fmaak_f32 v95, v252, v95, 0x40135761
	v_mul_f32_e32 v95, v100, v95
	v_exp_f32_e32 v134, v95
	v_mul_f32_e32 v95, v101, v101
	v_fmaak_f32 v95, v252, v95, 0x40135761
	v_mul_f32_e32 v95, v101, v95
	v_exp_f32_e32 v135, v95
	v_rcp_f32_e32 v95, v154
	v_add_f32_e32 v134, 1.0, v134
	v_rcp_f32_e32 v134, v134
	v_add_f32_e32 v135, 1.0, v135
	v_rcp_f32_e32 v135, v135
	v_pk_fma_f32 v[94:95], v[98:99], v[94:95], v[98:99] neg_lo:[1,0,0] neg_hi:[1,0,0]
	v_lshlrev_b32_e32 v98, 16, v156
	v_pk_mul_f32 v[78:79], v[78:79], v[94:95]
	v_pk_fma_f32 v[94:95], v[100:101], v[134:135], v[100:101] neg_lo:[1,0,0] neg_hi:[1,0,0]
	v_and_b32_e32 v99, 0xffff0000, v156
	v_pk_mul_f32 v[80:81], v[80:81], v[94:95]
	v_lshlrev_b32_e32 v94, 16, v96
	v_and_b32_e32 v95, 0xffff0000, v96
	v_pk_fma_f32 v[94:95], v[102:103], v[94:95], v[114:115]
	v_lshlrev_b32_e32 v100, 16, v166
	v_and_b32_e32 v101, 0xffff0000, v166
	v_pk_fma_f32 v[94:95], v[106:107], v[98:99], v[94:95]
	v_cvt_pk_bf16_f32 v78, v78, v79
	v_pk_fma_f32 v[94:95], v[110:111], v[100:101], v[94:95]
	v_and_b32_e32 v99, 0xffff0000, v157
	v_mul_f32_e32 v79, v94, v94
	v_fmaak_f32 v79, v252, v79, 0x40135761
	v_mul_f32_e32 v79, v94, v79
	v_exp_f32_e32 v96, v79
	v_mul_f32_e32 v79, v95, v95
	v_fmaak_f32 v79, v252, v79, 0x40135761
	v_mul_f32_e32 v79, v95, v79
	v_exp_f32_e32 v98, v79
	v_cvt_pk_bf16_f32 v79, v80, v81
	v_add_f32_e32 v80, 1.0, v96
	v_lshlrev_b32_e32 v96, 16, v97
	v_and_b32_e32 v97, 0xffff0000, v97
	v_add_f32_e32 v81, 1.0, v98
	v_lshlrev_b32_e32 v98, 16, v157
	v_pk_fma_f32 v[96:97], v[104:105], v[96:97], v[116:117]
	v_lshlrev_b32_e32 v100, 16, v167
	v_and_b32_e32 v101, 0xffff0000, v167
	v_pk_fma_f32 v[96:97], v[108:109], v[98:99], v[96:97]
	v_rcp_f32_e32 v80, v80
	v_pk_fma_f32 v[96:97], v[112:113], v[100:101], v[96:97]
	v_rcp_f32_e32 v81, v81
	v_mul_f32_e32 v98, v96, v96
	v_mul_f32_e32 v99, v97, v97
	v_fmaak_f32 v98, v252, v98, 0x40135761
	v_fmaak_f32 v99, v252, v99, 0x40135761
	v_mul_f32_e32 v98, v96, v98
	v_mul_f32_e32 v99, v97, v99
	v_exp_f32_e32 v98, v98
	v_exp_f32_e32 v99, v99
	v_pk_fma_f32 v[80:81], v[94:95], v[80:81], v[94:95] neg_lo:[1,0,0] neg_hi:[1,0,0]
	s_waitcnt vmcnt(0)
;     DI void operator()(const AccT& acc, const Unit& u, int wr, int wc, int fr, int fq) const {
;     ...
;         for (int bj = 0; bj < 2; ++bj) {
;             const int col = u.pn * 256 + bj * 128 + wc * 32 + 8 * fq;
;             f32x4 w0[2], w1[2], w2[2], cb[2];
; #pragma unroll
;             for (int hh = 0; hh < 2; ++hh) { w0[hh] = *(const f32x4*)(conv_w + col + 4 * hh); w1[hh] = *(const f32x4*)(conv_w + FF + col + 4 * hh); w2[hh] = *(const f32x4*)(conv_w + 2 * FF + col + 4 * hh); cb[hh] = *(const f32x4*)(conv_b + col + 4 * hh); }
; #pragma unroll
;             for (int aim = 0; aim < 4; ++aim) { const int ai = aim >> 1, mb = (aim & 1) * 2;
;                 u32x4 a0[4], a1[4], a2[4];
; #pragma unroll
;                 for (int m = mb; m < mb + 2; ++m) {
;                     const int row = rowbase + ai * 128 + m * 16; const int sq = row & (SEQ - 1);
;                     const bf16_t* pa = A + (size_t)row * FF + col;
;                     a0[m] = *(const u32x4*)pa;
;                     a1[m] = *(const u32x4*)(pa - (sq >= 1 ? FF : 0));
;                     a2[m] = *(const u32x4*)(pa - (sq >= 2 ? 2 * FF : 0));
;                 }
; #pragma unroll
;                 for (int m = mb; m < mb + 2; ++m) {
;                     const int row = rowbase + ai * 128 + m * 16; const int sq = row & (SEQ - 1);
;                     const float k1 = sq >= 1 ? 1.0f : 0.0f, k2 = sq >= 2 ? 1.0f : 0.0f;
;                     const u32x4 x0 = a0[m], x1 = a1[m], x2 = a2[m];
;                     const float f0[8] = {bflo(x0.x), bfhi(x0.x), bflo(x0.y), bfhi(x0.y), bflo(x0.z), bfhi(x0.z), bflo(x0.w), bfhi(x0.w)};
;                     const float f1[8] = {bflo(x1.x), bfhi(x1.x), bflo(x1.y), bfhi(x1.y), bflo(x1.z), bfhi(x1.z), bflo(x1.w), bfhi(x1.w)};
;                     const float f2[8] = {bflo(x2.x), bfhi(x2.x), bflo(x2.y), bfhi(x2.y), bflo(x2.z), bfhi(x2.z), bflo(x2.w), bfhi(x2.w)};
;                     f32x4 o0, o1;
; #pragma unroll
;                     for (int j = 0; j < 4; ++j) {
;                         const float c0 = cb[0][j] + w0[0][j] * f0[j] + k1 * (w1[0][j] * f1[j]) + k2 * (w2[0][j] * f2[j]);
;                         const float c1 = cb[1][j] + w0[1][j] * f0[4 + j] + k1 * (w1[1][j] * f1[4 + j]) + k2 * (w2[1][j] * f2[4 + j]);
;                         o0[j] = gelu_tanh(c0) * acc[ai][bj][m][0][j]; o1[j] = gelu_tanh(c1) * acc[ai][bj][m][1][j];
	v_lshlrev_b32_e32 v94, 16, v86
	v_add_f32_e32 v98, 1.0, v98
	v_add_f32_e32 v99, 1.0, v99
	v_rcp_f32_e32 v98, v98
	v_rcp_f32_e32 v99, v99
	v_pk_mul_f32 v[74:75], v[74:75], v[80:81]
	v_and_b32_e32 v95, 0xffff0000, v86
	v_cvt_pk_bf16_f32 v80, v74, v75
	v_pk_fma_f32 v[74:75], v[96:97], v[98:99], v[96:97] neg_lo:[1,0,0] neg_hi:[1,0,0]
	s_nop 0
	v_pk_mul_f32 v[74:75], v[76:77], v[74:75]
	v_lshlrev_b32_e32 v76, 16, v90
	v_cvt_pk_bf16_f32 v81, v74, v75
	v_mad_i64_i32 v[74:75], s[0:1], v139, s60, v[202:203]
	v_lshl_add_u64 v[134:135], v[74:75], 0, v[198:199]
	v_lshlrev_b32_e32 v74, 16, v82
	v_and_b32_e32 v75, 0xffff0000, v82
	v_and_b32_e32 v77, 0xffff0000, v90
	v_pk_fma_f32 v[74:75], v[118:119], v[74:75], v[122:123]
	global_store_dwordx4 v[134:135], v[78:81], off
	v_pk_fma_f32 v[74:75], v[126:127], v[76:77], v[74:75]
	v_lshlrev_b32_e32 v82, 16, v87
	v_lshlrev_b32_e32 v78, 16, v83
	v_and_b32_e32 v79, 0xffff0000, v83
	v_lshlrev_b32_e32 v80, 16, v91
	v_and_b32_e32 v81, 0xffff0000, v91
	v_pk_fma_f32 v[78:79], v[120:121], v[78:79], v[124:125]
	v_pk_fma_f32 v[74:75], v[130:131], v[94:95], v[74:75]
	v_and_b32_e32 v83, 0xffff0000, v87
	v_pk_fma_f32 v[78:79], v[128:129], v[80:81], v[78:79]
	v_mul_f32_e32 v76, v74, v74
	v_mul_f32_e32 v77, v75, v75
	v_pk_fma_f32 v[78:79], v[132:133], v[82:83], v[78:79]
	v_fmaak_f32 v76, v252, v76, 0x40135761
	v_fmaak_f32 v77, v252, v77, 0x40135761
	v_mul_f32_e32 v80, v78, v78
	v_mul_f32_e32 v81, v79, v79
	v_mul_f32_e32 v76, v74, v76
	v_mul_f32_e32 v77, v75, v77
	v_fmaak_f32 v80, v252, v80, 0x40135761
	v_fmaak_f32 v81, v252, v81, 0x40135761
	v_mul_f32_e32 v80, v78, v80
	v_mul_f32_e32 v81, v79, v81
	v_exp_f32_e32 v76, v76
	v_exp_f32_e32 v77, v77
	v_exp_f32_e32 v80, v80
	v_exp_f32_e32 v81, v81
	v_add_f32_e32 v76, 1.0, v76
	v_add_f32_e32 v77, 1.0, v77
	v_rcp_f32_e32 v76, v76
	v_rcp_f32_e32 v77, v77
	v_add_f32_e32 v80, 1.0, v80
	v_add_f32_e32 v81, 1.0, v81
	v_rcp_f32_e32 v80, v80
	v_rcp_f32_e32 v81, v81
	v_pk_fma_f32 v[74:75], v[74:75], v[76:77], v[74:75] neg_lo:[1,0,0] neg_hi:[1,0,0]
	v_lshlrev_b32_e32 v76, 16, v92
	v_pk_mul_f32 v[70:71], v[70:71], v[74:75]
	v_pk_fma_f32 v[74:75], v[78:79], v[80:81], v[78:79] neg_lo:[1,0,0] neg_hi:[1,0,0]
	v_and_b32_e32 v77, 0xffff0000, v92
	v_pk_mul_f32 v[72:73], v[72:73], v[74:75]
	v_lshlrev_b32_e32 v74, 16, v84
	v_and_b32_e32 v75, 0xffff0000, v84
	v_pk_fma_f32 v[74:75], v[102:103], v[74:75], v[114:115]
	v_lshlrev_b32_e32 v78, 16, v88
	v_and_b32_e32 v79, 0xffff0000, v88
	v_pk_fma_f32 v[74:75], v[106:107], v[76:77], v[74:75]
	v_cvt_pk_bf16_f32 v70, v70, v71
	v_pk_fma_f32 v[74:75], v[110:111], v[78:79], v[74:75]
	v_lshlrev_b32_e32 v78, 16, v93
	v_mul_f32_e32 v71, v74, v74
	v_fmaak_f32 v71, v252, v71, 0x40135761
	v_mul_f32_e32 v71, v74, v71
	v_exp_f32_e32 v76, v71
	v_mul_f32_e32 v71, v75, v75
	v_fmaak_f32 v71, v252, v71, 0x40135761
	v_mul_f32_e32 v71, v75, v71
	v_exp_f32_e32 v77, v71
	v_cvt_pk_bf16_f32 v71, v72, v73
	v_add_f32_e32 v72, 1.0, v76
	v_lshlrev_b32_e32 v76, 16, v85
	v_add_f32_e32 v73, 1.0, v77
	v_and_b32_e32 v77, 0xffff0000, v85
	v_and_b32_e32 v79, 0xffff0000, v93
	v_pk_fma_f32 v[76:77], v[104:105], v[76:77], v[116:117]
	v_lshlrev_b32_e32 v80, 16, v89
	v_and_b32_e32 v81, 0xffff0000, v89
	v_pk_fma_f32 v[76:77], v[108:109], v[78:79], v[76:77]
	v_rcp_f32_e32 v72, v72
	v_pk_fma_f32 v[76:77], v[112:113], v[80:81], v[76:77]
	v_rcp_f32_e32 v73, v73
	v_mul_f32_e32 v78, v76, v76
	v_mul_f32_e32 v79, v77, v77
	v_fmaak_f32 v78, v252, v78, 0x40135761
	v_fmaak_f32 v79, v252, v79, 0x40135761
	v_mul_f32_e32 v78, v76, v78
	v_mul_f32_e32 v79, v77, v79
	v_exp_f32_e32 v78, v78
	v_exp_f32_e32 v79, v79
	v_pk_fma_f32 v[72:73], v[74:75], v[72:73], v[74:75] neg_lo:[1,0,0] neg_hi:[1,0,0]
	v_mov_b64_e32 v[112:113], s[12:13]
	v_add_f32_e32 v78, 1.0, v78
	v_add_f32_e32 v79, 1.0, v79
	v_rcp_f32_e32 v78, v78
	v_rcp_f32_e32 v79, v79
	v_pk_mul_f32 v[66:67], v[66:67], v[72:73]
	v_mad_i64_i32 v[98:99], s[0:1], v193, s60, v[112:113]
	v_cvt_pk_bf16_f32 v72, v66, v67
	v_pk_fma_f32 v[66:67], v[76:77], v[78:79], v[76:77] neg_lo:[1,0,0] neg_hi:[1,0,0]
	s_nop 0
	v_pk_mul_f32 v[66:67], v[68:69], v[66:67]
	s_nop 0
	v_cvt_pk_bf16_f32 v73, v66, v67
	v_mad_i64_i32 v[66:67], s[0:1], v138, s60, v[202:203]
	v_lshl_add_u64 v[110:111], v[66:67], 0, v[198:199]
	v_or_b32_e32 v66, 0x80, v192
	v_ashrrev_i32_e32 v67, 31, v66
	global_store_dwordx4 v[110:111], v[70:73], off
	v_lshlrev_b64 v[114:115], 1, v[66:67]
	v_lshlrev_b64 v[68:69], 2, v[66:67]
	v_mad_i64_i32 v[70:71], s[0:1], v212, s60, v[112:113]
	v_lshl_add_u64 v[66:67], v[70:71], 0, v[114:115]
	v_lshl_add_u64 v[72:73], v[70:71], 0, v[194:195]
	v_lshl_add_u64 v[72:73], v[72:73], 0, v[114:115]
	global_load_dwordx4 v[116:119], v[66:67], off
	global_load_dwordx4 v[120:123], v[72:73], off
	v_lshl_add_u64 v[66:67], v[70:71], 0, v[196:197]
	v_lshl_add_u64 v[66:67], v[66:67], 0, v[114:115]
	v_lshl_add_u64 v[78:79], s[20:21], 0, v[68:69]
	global_load_dwordx4 v[124:127], v[66:67], off
	global_load_dwordx4 v[82:85], v[188:189], off offset:512
	global_load_dwordx4 v[90:93], v[190:191], off offset:512
	global_load_dwordx4 v[86:89], v[78:79], off
	v_lshl_add_u64 v[66:67], s[22:23], 0, v[68:69]
	global_load_dwordx4 v[94:97], v[66:67], off
	global_load_dwordx4 v[70:73], v[188:189], off offset:528
	s_nop 0
	global_load_dwordx4 v[66:69], v[66:67], off offset:16
	s_nop 0
	global_load_dwordx4 v[74:77], v[190:191], off offset:528
	s_nop 0
	global_load_dwordx4 v[78:81], v[78:79], off offset:16
	v_lshl_add_u64 v[102:103], v[98:99], 0, v[114:115]
	v_add_co_u32_e32 v104, vcc, s61, v102
	global_load_dwordx4 v[98:101], v[102:103], off
	s_nop 0
	v_addc_co_u32_e32 v105, vcc, -1, v103, vcc
	v_add_co_u32_e32 v102, vcc, s62, v102
	s_waitcnt vmcnt(11)
; DI float bflo(unsigned w) { return __uint_as_float(w << 16); }
; DI float bfhi(unsigned w) { return __uint_as_float(w & 0xffff0000u); }
; DI float gelu_tanh(float v) {
;     const float uu = 0.7978845608028654f * (v + 0.044715f * v * v * v);
;     const float e = __builtin_amdgcn_exp2f(2.8853900817779268f * uu);
;     return v - v * __builtin_amdgcn_rcpf(e + 1.0f);
;     DI void operator()(const AccT& acc, const Unit& u, int wr, int wc, int fr, int fq) const {
;     ...
;                 for (int m = mb; m < mb + 2; ++m) {
;                     const int row = rowbase + ai * 128 + m * 16; const int sq = row & (SEQ - 1);
;                     const bf16_t* pa = A + (size_t)row * FF + col;
;                     a0[m] = *(const u32x4*)pa;
;                     a1[m] = *(const u32x4*)(pa - (sq >= 1 ? FF : 0));
;                     a2[m] = *(const u32x4*)(pa - (sq >= 2 ? 2 * FF : 0));
;                 }
; #pragma unroll
;                 for (int m = mb; m < mb + 2; ++m) {
;                     const int row = rowbase + ai * 128 + m * 16; const int sq = row & (SEQ - 1);
;                     const float k1 = sq >= 1 ? 1.0f : 0.0f, k2 = sq >= 2 ? 1.0f : 0.0f;
;                     const u32x4 x0 = a0[m], x1 = a1[m], x2 = a2[m];
;                     const float f0[8] = {bflo(x0.x), bfhi(x0.x), bflo(x0.y), bfhi(x0.y), bflo(x0.z), bfhi(x0.z), bflo(x0.w), bfhi(x0.w)};
;                     const float f1[8] = {bflo(x1.x), bfhi(x1.x), bflo(x1.y), bfhi(x1.y), bflo(x1.z), bfhi(x1.z), bflo(x1.w), bfhi(x1.w)};
;                     const float f2[8] = {bflo(x2.x), bfhi(x2.x), bflo(x2.y), bfhi(x2.y), bflo(x2.z), bfhi(x2.z), bflo(x2.w), bfhi(x2.w)};
;                     f32x4 o0, o1;
; #pragma unroll
;                     for (int j = 0; j < 4; ++j) {
;                         const float c0 = cb[0][j] + w0[0][j] * f0[j] + k1 * (w1[0][j] * f1[j]) + k2 * (w2[0][j] * f2[j]);
;                         const float c1 = cb[1][j] + w0[1][j] * f0[4 + j] + k1 * (w1[1][j] * f1[4 + j]) + k2 * (w2[1][j] * f2[4 + j]);
;                         o0[j] = gelu_tanh(c0) * acc[ai][bj][m][0][j]; o1[j] = gelu_tanh(c1) * acc[ai][bj][m][1][j];
;                     }
;                     *(u32x4*)(ACT + (size_t)row * FF + col) = pack8(o0, o1);
	v_lshlrev_b32_e32 v106, 16, v116
	v_and_b32_e32 v107, 0xffff0000, v116
	s_waitcnt vmcnt(10)
	v_lshlrev_b32_e32 v108, 16, v120
	v_and_b32_e32 v109, 0xffff0000, v120
	s_waitcnt vmcnt(9)
	v_lshlrev_b32_e32 v128, 16, v124
	v_and_b32_e32 v129, 0xffff0000, v124
	s_waitcnt vmcnt(7)
	v_pk_fma_f32 v[106:107], v[82:83], v[106:107], v[90:91]
	s_waitcnt vmcnt(6)
	v_pk_mul_f32 v[108:109], v[86:87], v[108:109]
	v_addc_co_u32_e32 v103, vcc, -1, v103, vcc
	v_pk_fma_f32 v[106:107], v[186:187], v[108:109], v[106:107] op_sel_hi:[0,1,1]
	s_waitcnt vmcnt(5)
	v_pk_mul_f32 v[108:109], v[94:95], v[128:129]
	v_lshlrev_b32_e32 v130, 16, v117
	v_pk_fma_f32 v[128:129], v[184:185], v[108:109], v[106:107] op_sel_hi:[0,1,1]
	v_mul_f32_e32 v106, v128, v128
	v_fmaak_f32 v106, v252, v106, 0x40135761
	v_mul_f32_e32 v106, v128, v106
	v_exp_f32_e32 v116, v106
	v_mul_f32_e32 v106, v129, v129
	v_fmaak_f32 v106, v252, v106, 0x40135761
	v_mul_f32_e32 v106, v129, v106
	v_exp_f32_e32 v120, v106
	global_load_dwordx4 v[106:109], v[104:105], off offset:-3072
	s_nop 0
	global_load_dwordx4 v[102:105], v[102:103], off offset:-2048
	v_and_b32_e32 v131, 0xffff0000, v117
	v_lshlrev_b32_e32 v124, 16, v125
	v_add_f32_e32 v132, 1.0, v120
	v_lshlrev_b32_e32 v120, 16, v121
	v_and_b32_e32 v121, 0xffff0000, v121
	v_and_b32_e32 v125, 0xffff0000, v125
	v_pk_fma_f32 v[130:131], v[84:85], v[130:131], v[92:93]
	v_pk_mul_f32 v[120:121], v[88:89], v[120:121]
	v_pk_mul_f32 v[124:125], v[96:97], v[124:125]
	v_pk_fma_f32 v[120:121], v[186:187], v[120:121], v[130:131] op_sel_hi:[0,1,1]
	v_pk_fma_f32 v[120:121], v[184:185], v[124:125], v[120:121] op_sel_hi:[0,1,1]
	v_mul_f32_e32 v117, v120, v120
	v_fmaak_f32 v117, v252, v117, 0x40135761
	v_mul_f32_e32 v117, v120, v117
	v_exp_f32_e32 v124, v117
	v_mul_f32_e32 v117, v121, v121
	v_fmaak_f32 v117, v252, v117, 0x40135761
	v_mul_f32_e32 v117, v121, v117
	v_exp_f32_e32 v125, v117
	v_add_f32_e32 v116, 1.0, v116
	v_rcp_f32_e32 v116, v116
	v_rcp_f32_e32 v117, v132
	v_add_f32_e32 v124, 1.0, v124
	v_add_f32_e32 v125, 1.0, v125
	v_rcp_f32_e32 v124, v124
	v_rcp_f32_e32 v125, v125
	v_pk_fma_f32 v[116:117], v[128:129], v[116:117], v[128:129] neg_lo:[1,0,0] neg_hi:[1,0,0]
	s_nop 0
	v_pk_mul_f32 v[62:63], v[62:63], v[116:117]
	v_pk_fma_f32 v[116:117], v[120:121], v[124:125], v[120:121] neg_lo:[1,0,0] neg_hi:[1,0,0]
	v_lshlrev_b32_e32 v120, 16, v122
	v_pk_mul_f32 v[64:65], v[64:65], v[116:117]
	v_lshlrev_b32_e32 v116, 16, v118
	v_and_b32_e32 v117, 0xffff0000, v118
	v_and_b32_e32 v121, 0xffff0000, v122
	v_lshlrev_b32_e32 v124, 16, v126
	v_and_b32_e32 v125, 0xffff0000, v126
	s_waitcnt vmcnt(4)
	v_pk_fma_f32 v[116:117], v[70:71], v[116:117], v[74:75]
	s_waitcnt vmcnt(3)
	v_pk_mul_f32 v[120:121], v[78:79], v[120:121]
	v_cvt_pk_bf16_f32 v62, v62, v63
	v_pk_fma_f32 v[116:117], v[186:187], v[120:121], v[116:117] op_sel_hi:[0,1,1]
	v_pk_mul_f32 v[120:121], v[66:67], v[124:125]
	v_lshlrev_b32_e32 v122, 16, v127
	v_pk_fma_f32 v[116:117], v[184:185], v[120:121], v[116:117] op_sel_hi:[0,1,1]
	v_mul_f32_e32 v63, v116, v116
	v_fmaak_f32 v63, v252, v63, 0x40135761
	v_mul_f32_e32 v63, v116, v63
	v_exp_f32_e32 v118, v63
	v_mul_f32_e32 v63, v117, v117
	v_fmaak_f32 v63, v252, v63, 0x40135761
	v_mul_f32_e32 v63, v117, v63
	v_exp_f32_e32 v120, v63
	v_cvt_pk_bf16_f32 v63, v64, v65
	v_add_f32_e32 v64, 1.0, v118
	v_lshlrev_b32_e32 v118, 16, v119
	v_add_f32_e32 v65, 1.0, v120
	v_and_b32_e32 v119, 0xffff0000, v119
	v_lshlrev_b32_e32 v120, 16, v123
	v_and_b32_e32 v121, 0xffff0000, v123
	v_and_b32_e32 v123, 0xffff0000, v127
	v_pk_fma_f32 v[118:119], v[72:73], v[118:119], v[76:77]
	v_pk_mul_f32 v[120:121], v[80:81], v[120:121]
	v_rcp_f32_e32 v64, v64
	v_pk_fma_f32 v[118:119], v[186:187], v[120:121], v[118:119] op_sel_hi:[0,1,1]
	v_pk_mul_f32 v[120:121], v[68:69], v[122:123]
	v_rcp_f32_e32 v65, v65
	v_pk_fma_f32 v[118:119], v[184:185], v[120:121], v[118:119] op_sel_hi:[0,1,1]
	v_mul_f32_e32 v120, v118, v118
	v_mul_f32_e32 v121, v119, v119
	v_fmaak_f32 v120, v252, v120, 0x40135761
	v_fmaak_f32 v121, v252, v121, 0x40135761
	v_mul_f32_e32 v120, v118, v120
	v_mul_f32_e32 v121, v119, v121
	v_exp_f32_e32 v120, v120
	v_exp_f32_e32 v121, v121
	v_pk_fma_f32 v[64:65], v[116:117], v[64:65], v[116:117] neg_lo:[1,0,0] neg_hi:[1,0,0]
	s_waitcnt vmcnt(0)
; DI float bflo(unsigned w) { return __uint_as_float(w << 16); }
; DI float gelu_tanh(float v) {
;     const float uu = 0.7978845608028654f * (v + 0.044715f * v * v * v);
;     const float e = __builtin_amdgcn_exp2f(2.8853900817779268f * uu);
;     return v - v * __builtin_amdgcn_rcpf(e + 1.0f);
; }
;     DI void operator()(const AccT& acc, const Unit& u, int wr, int wc, int fr, int fq) const {
;     ...
;             for (int aim = 0; aim < 4; ++aim) { const int ai = aim >> 1, mb = (aim & 1) * 2;
;                 u32x4 a0[4], a1[4], a2[4];
; #pragma unroll
;                 for (int m = mb; m < mb + 2; ++m) {
;                     const int row = rowbase + ai * 128 + m * 16; const int sq = row & (SEQ - 1);
;                     const bf16_t* pa = A + (size_t)row * FF + col;
;                     a0[m] = *(const u32x4*)pa;
;                     a1[m] = *(const u32x4*)(pa - (sq >= 1 ? FF : 0));
;                     a2[m] = *(const u32x4*)(pa - (sq >= 2 ? 2 * FF : 0));
;                 }
; #pragma unroll
;                 for (int m = mb; m < mb + 2; ++m) {
;                     const int row = rowbase + ai * 128 + m * 16; const int sq = row & (SEQ - 1);
;                     const float k1 = sq >= 1 ? 1.0f : 0.0f, k2 = sq >= 2 ? 1.0f : 0.0f;
;                     const u32x4 x0 = a0[m], x1 = a1[m], x2 = a2[m];
;                     const float f0[8] = {bflo(x0.x), bfhi(x0.x), bflo(x0.y), bfhi(x0.y), bflo(x0.z), bfhi(x0.z), bflo(x0.w), bfhi(x0.w)};
;                     const float f1[8] = {bflo(x1.x), bfhi(x1.x), bflo(x1.y), bfhi(x1.y), bflo(x1.z), bfhi(x1.z), bflo(x1.w), bfhi(x1.w)};
;                     const float f2[8] = {bflo(x2.x), bfhi(x2.x), bflo(x2.y), bfhi(x2.y), bflo(x2.z), bfhi(x2.z), bflo(x2.w), bfhi(x2.w)};
;                     f32x4 o0, o1;
; #pragma unroll
;                     for (int j = 0; j < 4; ++j) {
;                         const float c0 = cb[0][j] + w0[0][j] * f0[j] + k1 * (w1[0][j] * f1[j]) + k2 * (w2[0][j] * f2[j]);
;                         const float c1 = cb[1][j] + w0[1][j] * f0[4 + j] + k1 * (w1[1][j] * f1[4 + j]) + k2 * (w2[1][j] * f2[4 + j]);
;                         o0[j] = gelu_tanh(c0) * acc[ai][bj][m][0][j]; o1[j] = gelu_tanh(c1) * acc[ai][bj][m][1][j];
;                     }
;                     *(u32x4*)(ACT + (size_t)row * FF + col) = pack8(o0, o1);
;                 }
	v_lshlrev_b32_e32 v116, 16, v102
	v_add_f32_e32 v120, 1.0, v120
	v_add_f32_e32 v121, 1.0, v121
	v_rcp_f32_e32 v120, v120
	v_rcp_f32_e32 v121, v121
	v_pk_mul_f32 v[58:59], v[58:59], v[64:65]
	v_and_b32_e32 v117, 0xffff0000, v102
	v_cvt_pk_bf16_f32 v64, v58, v59
	v_pk_fma_f32 v[58:59], v[118:119], v[120:121], v[118:119] neg_lo:[1,0,0] neg_hi:[1,0,0]
	s_nop 0
	v_pk_mul_f32 v[58:59], v[60:61], v[58:59]
	v_lshlrev_b32_e32 v60, 16, v106
	v_cvt_pk_bf16_f32 v65, v58, v59
	global_store_dwordx4 v[200:201], v[62:65], off offset:256
	v_lshlrev_b32_e32 v58, 16, v98
	v_and_b32_e32 v59, 0xffff0000, v98
	v_lshlrev_b32_e32 v62, 16, v99
	v_and_b32_e32 v63, 0xffff0000, v99
	v_lshlrev_b32_e32 v64, 16, v107
	v_and_b32_e32 v65, 0xffff0000, v107
	v_pk_fma_f32 v[62:63], v[84:85], v[62:63], v[92:93]
	v_lshlrev_b32_e32 v98, 16, v103
	v_and_b32_e32 v99, 0xffff0000, v103
	v_pk_fma_f32 v[62:63], v[88:89], v[64:65], v[62:63]
	v_and_b32_e32 v61, 0xffff0000, v106
	v_pk_fma_f32 v[98:99], v[96:97], v[98:99], v[62:63]
	v_pk_fma_f32 v[58:59], v[82:83], v[58:59], v[90:91]
	v_mul_f32_e32 v62, v98, v98
	v_fmaak_f32 v62, v252, v62, 0x40135761
	v_mul_f32_e32 v63, v99, v99
	v_mul_f32_e32 v62, v98, v62
	v_fmaak_f32 v63, v252, v63, 0x40135761
	v_mul_f32_e32 v63, v99, v63
	v_exp_f32_e32 v62, v62
	v_exp_f32_e32 v63, v63
	v_pk_fma_f32 v[58:59], v[86:87], v[60:61], v[58:59]
	v_add_f32_e32 v62, 1.0, v62
	v_rcp_f32_e32 v102, v62
	v_add_f32_e32 v62, 1.0, v63
	v_rcp_f32_e32 v103, v62
	v_mad_i64_i32 v[62:63], s[0:1], v163, s60, v[112:113]
	v_lshl_add_u64 v[106:107], v[62:63], 0, v[114:115]
	v_pk_fma_f32 v[58:59], v[94:95], v[116:117], v[58:59]
	v_add_co_u32_e32 v116, vcc, s61, v106
	v_mul_f32_e32 v60, v58, v58
	s_nop 0
	v_addc_co_u32_e32 v117, vcc, -1, v107, vcc
	global_load_dwordx4 v[62:65], v[106:107], off
	s_nop 0
	global_load_dwordx4 v[116:119], v[116:117], off offset:-3072
	v_add_co_u32_e32 v106, vcc, s62, v106
	v_mul_f32_e32 v61, v59, v59
	s_nop 0
	v_addc_co_u32_e32 v107, vcc, -1, v107, vcc
	global_load_dwordx4 v[120:123], v[106:107], off offset:-2048
	v_fmaak_f32 v60, v252, v60, 0x40135761
	v_fmaak_f32 v61, v252, v61, 0x40135761
	v_mul_f32_e32 v60, v58, v60
	v_mul_f32_e32 v61, v59, v61
	v_exp_f32_e32 v60, v60
	v_exp_f32_e32 v61, v61
	v_add_f32_e32 v60, 1.0, v60
	v_add_f32_e32 v61, 1.0, v61
	v_rcp_f32_e32 v60, v60
	v_rcp_f32_e32 v61, v61
	s_nop 0
	v_pk_fma_f32 v[58:59], v[58:59], v[60:61], v[58:59] neg_lo:[1,0,0] neg_hi:[1,0,0]
	s_nop 0
	v_pk_mul_f32 v[54:55], v[54:55], v[58:59]
	v_pk_fma_f32 v[58:59], v[98:99], v[102:103], v[98:99] neg_lo:[1,0,0] neg_hi:[1,0,0]
	v_lshlrev_b32_e32 v60, 16, v108
	v_pk_mul_f32 v[56:57], v[56:57], v[58:59]
	v_lshlrev_b32_e32 v58, 16, v100
	v_and_b32_e32 v59, 0xffff0000, v100
	v_and_b32_e32 v61, 0xffff0000, v108
	v_pk_fma_f32 v[58:59], v[70:71], v[58:59], v[74:75]
	v_lshlrev_b32_e32 v98, 16, v104
	v_and_b32_e32 v99, 0xffff0000, v104
	v_pk_fma_f32 v[58:59], v[78:79], v[60:61], v[58:59]
	v_cvt_pk_bf16_f32 v54, v54, v55
	v_pk_fma_f32 v[58:59], v[66:67], v[98:99], v[58:59]
	v_lshlrev_b32_e32 v98, 16, v109
	v_mul_f32_e32 v55, v58, v58
	v_fmaak_f32 v55, v252, v55, 0x40135761
	v_mul_f32_e32 v55, v58, v55
	v_exp_f32_e32 v60, v55
	v_mul_f32_e32 v55, v59, v59
	v_fmaak_f32 v55, v252, v55, 0x40135761
	v_mul_f32_e32 v55, v59, v55
	v_exp_f32_e32 v61, v55
	v_cvt_pk_bf16_f32 v55, v56, v57
	v_add_f32_e32 v56, 1.0, v60
	v_lshlrev_b32_e32 v60, 16, v101
	v_add_f32_e32 v57, 1.0, v61
	v_and_b32_e32 v61, 0xffff0000, v101
	v_and_b32_e32 v99, 0xffff0000, v109
	v_pk_fma_f32 v[60:61], v[72:73], v[60:61], v[76:77]
	v_lshlrev_b32_e32 v100, 16, v105
	v_and_b32_e32 v101, 0xffff0000, v105
	v_pk_fma_f32 v[60:61], v[80:81], v[98:99], v[60:61]
	v_rcp_f32_e32 v56, v56
	v_pk_fma_f32 v[60:61], v[68:69], v[100:101], v[60:61]
	v_rcp_f32_e32 v57, v57
	v_mul_f32_e32 v98, v60, v60
	v_mul_f32_e32 v99, v61, v61
	v_fmaak_f32 v98, v252, v98, 0x40135761
	v_fmaak_f32 v99, v252, v99, 0x40135761
	v_mul_f32_e32 v98, v60, v98
	v_mul_f32_e32 v99, v61, v99
	v_exp_f32_e32 v98, v98
	v_exp_f32_e32 v99, v99
	v_pk_fma_f32 v[56:57], v[58:59], v[56:57], v[58:59] neg_lo:[1,0,0] neg_hi:[1,0,0]
	s_waitcnt vmcnt(2)
	v_lshlrev_b32_e32 v58, 16, v62
	v_add_f32_e32 v98, 1.0, v98
	v_add_f32_e32 v99, 1.0, v99
	v_rcp_f32_e32 v98, v98
	v_rcp_f32_e32 v99, v99
	v_pk_mul_f32 v[50:51], v[50:51], v[56:57]
	v_and_b32_e32 v59, 0xffff0000, v62
	v_cvt_pk_bf16_f32 v56, v50, v51
	v_pk_fma_f32 v[50:51], v[60:61], v[98:99], v[60:61] neg_lo:[1,0,0] neg_hi:[1,0,0]
	s_waitcnt vmcnt(1)
	v_lshlrev_b32_e32 v60, 16, v116
	v_pk_mul_f32 v[50:51], v[52:53], v[50:51]
	v_and_b32_e32 v61, 0xffff0000, v116
	v_cvt_pk_bf16_f32 v57, v50, v51
	v_mad_i64_i32 v[50:51], s[0:1], v162, s60, v[112:113]
	global_store_dwordx4 v[160:161], v[54:57], off offset:256
	v_pk_fma_f32 v[58:59], v[82:83], v[58:59], v[90:91]
	v_and_b32_e32 v101, 0xffff0000, v63
	v_lshl_add_u64 v[54:55], v[50:51], 0, v[114:115]
	global_load_dwordx4 v[50:53], v[54:55], off
	s_waitcnt vmcnt(2)
; DI float bflo(unsigned w) { return __uint_as_float(w << 16); }
; DI float gelu_tanh(float v) {
;     const float uu = 0.7978845608028654f * (v + 0.044715f * v * v * v);
;     const float e = __builtin_amdgcn_exp2f(2.8853900817779268f * uu);
;     return v - v * __builtin_amdgcn_rcpf(e + 1.0f);
; }
;     DI void operator()(const AccT& acc, const Unit& u, int wr, int wc, int fr, int fq) const {
;     ...
;             for (int aim = 0; aim < 4; ++aim) { const int ai = aim >> 1, mb = (aim & 1) * 2;
;                 u32x4 a0[4], a1[4], a2[4];
; #pragma unroll
;                 for (int m = mb; m < mb + 2; ++m) {
;                     const int row = rowbase + ai * 128 + m * 16; const int sq = row & (SEQ - 1);
;                     const bf16_t* pa = A + (size_t)row * FF + col;
;                     a0[m] = *(const u32x4*)pa;
;                     a1[m] = *(const u32x4*)(pa - (sq >= 1 ? FF : 0));
;                     a2[m] = *(const u32x4*)(pa - (sq >= 2 ? 2 * FF : 0));
;                 }
; #pragma unroll
;                 for (int m = mb; m < mb + 2; ++m) {
;                     const int row = rowbase + ai * 128 + m * 16; const int sq = row & (SEQ - 1);
;                     const float k1 = sq >= 1 ? 1.0f : 0.0f, k2 = sq >= 2 ? 1.0f : 0.0f;
;                     const u32x4 x0 = a0[m], x1 = a1[m], x2 = a2[m];
;                     const float f0[8] = {bflo(x0.x), bfhi(x0.x), bflo(x0.y), bfhi(x0.y), bflo(x0.z), bfhi(x0.z), bflo(x0.w), bfhi(x0.w)};
;                     const float f1[8] = {bflo(x1.x), bfhi(x1.x), bflo(x1.y), bfhi(x1.y), bflo(x1.z), bfhi(x1.z), bflo(x1.w), bfhi(x1.w)};
;                     const float f2[8] = {bflo(x2.x), bfhi(x2.x), bflo(x2.y), bfhi(x2.y), bflo(x2.z), bfhi(x2.z), bflo(x2.w), bfhi(x2.w)};
;                     f32x4 o0, o1;
; #pragma unroll
;                     for (int j = 0; j < 4; ++j) {
;                         const float c0 = cb[0][j] + w0[0][j] * f0[j] + k1 * (w1[0][j] * f1[j]) + k2 * (w2[0][j] * f2[j]);
;                         const float c1 = cb[1][j] + w0[1][j] * f0[4 + j] + k1 * (w1[1][j] * f1[4 + j]) + k2 * (w2[1][j] * f2[4 + j]);
;                         o0[j] = gelu_tanh(c0) * acc[ai][bj][m][0][j]; o1[j] = gelu_tanh(c1) * acc[ai][bj][m][1][j];
;                     }
;                     *(u32x4*)(ACT + (size_t)row * FF + col) = pack8(o0, o1);
;                 }
	v_lshlrev_b32_e32 v98, 16, v120
	v_and_b32_e32 v99, 0xffff0000, v120
	v_pk_fma_f32 v[58:59], v[86:87], v[60:61], v[58:59]
	v_add_co_u32_e32 v56, vcc, s61, v54
	v_pk_fma_f32 v[98:99], v[94:95], v[98:99], v[58:59]
	s_nop 0
	v_addc_co_u32_e32 v57, vcc, -1, v55, vcc
	v_mul_f32_e32 v58, v98, v98
	v_fmaak_f32 v58, v252, v58, 0x40135761
	v_mul_f32_e32 v58, v98, v58
	v_exp_f32_e32 v62, v58
	v_mul_f32_e32 v58, v99, v99
	v_fmaak_f32 v58, v252, v58, 0x40135761
	v_mul_f32_e32 v58, v99, v58
	v_add_co_u32_e32 v54, vcc, s62, v54
	s_nop 0
	v_addc_co_u32_e32 v55, vcc, -1, v55, vcc
	v_exp_f32_e32 v100, v58
	global_load_dwordx4 v[58:61], v[56:57], off offset:-3072
	s_nop 0
	global_load_dwordx4 v[54:57], v[54:55], off offset:-2048
	v_lshlrev_b32_e32 v102, 16, v117
	v_and_b32_e32 v103, 0xffff0000, v117
	v_add_f32_e32 v106, 1.0, v100
	v_lshlrev_b32_e32 v100, 16, v63
	v_pk_fma_f32 v[100:101], v[84:85], v[100:101], v[92:93]
	v_lshlrev_b32_e32 v104, 16, v121
	v_and_b32_e32 v105, 0xffff0000, v121
	v_pk_fma_f32 v[100:101], v[88:89], v[102:103], v[100:101]
	v_add_f32_e32 v62, 1.0, v62
	v_pk_fma_f32 v[100:101], v[96:97], v[104:105], v[100:101]
	v_rcp_f32_e32 v62, v62
	v_mul_f32_e32 v63, v100, v100
	v_fmaak_f32 v63, v252, v63, 0x40135761
	v_mul_f32_e32 v63, v100, v63
	v_exp_f32_e32 v102, v63
	v_mul_f32_e32 v63, v101, v101
	v_fmaak_f32 v63, v252, v63, 0x40135761
	v_mul_f32_e32 v63, v101, v63
	v_exp_f32_e32 v103, v63
	v_rcp_f32_e32 v63, v106
	v_add_f32_e32 v102, 1.0, v102
	v_rcp_f32_e32 v102, v102
	v_add_f32_e32 v103, 1.0, v103
	v_rcp_f32_e32 v103, v103
	v_pk_fma_f32 v[62:63], v[98:99], v[62:63], v[98:99] neg_lo:[1,0,0] neg_hi:[1,0,0]
	v_lshlrev_b32_e32 v98, 16, v118
	v_pk_mul_f32 v[46:47], v[46:47], v[62:63]
	v_pk_fma_f32 v[62:63], v[100:101], v[102:103], v[100:101] neg_lo:[1,0,0] neg_hi:[1,0,0]
	v_and_b32_e32 v99, 0xffff0000, v118
	v_pk_mul_f32 v[48:49], v[48:49], v[62:63]
	v_lshlrev_b32_e32 v62, 16, v64
	v_and_b32_e32 v63, 0xffff0000, v64
	v_pk_fma_f32 v[62:63], v[70:71], v[62:63], v[74:75]
	v_lshlrev_b32_e32 v100, 16, v122
	v_and_b32_e32 v101, 0xffff0000, v122
	v_pk_fma_f32 v[62:63], v[78:79], v[98:99], v[62:63]
	v_cvt_pk_bf16_f32 v46, v46, v47
	v_pk_fma_f32 v[62:63], v[66:67], v[100:101], v[62:63]
	v_and_b32_e32 v99, 0xffff0000, v119
	v_mul_f32_e32 v47, v62, v62
	v_fmaak_f32 v47, v252, v47, 0x40135761
	v_mul_f32_e32 v47, v62, v47
	v_exp_f32_e32 v64, v47
	v_mul_f32_e32 v47, v63, v63
	v_fmaak_f32 v47, v252, v47, 0x40135761
	v_mul_f32_e32 v47, v63, v47
	v_exp_f32_e32 v98, v47
	v_cvt_pk_bf16_f32 v47, v48, v49
	v_add_f32_e32 v48, 1.0, v64
	v_lshlrev_b32_e32 v64, 16, v65
	v_and_b32_e32 v65, 0xffff0000, v65
	v_add_f32_e32 v49, 1.0, v98
	v_lshlrev_b32_e32 v98, 16, v119
	v_pk_fma_f32 v[64:65], v[72:73], v[64:65], v[76:77]
	v_lshlrev_b32_e32 v100, 16, v123
	v_and_b32_e32 v101, 0xffff0000, v123
	v_pk_fma_f32 v[64:65], v[80:81], v[98:99], v[64:65]
	v_rcp_f32_e32 v48, v48
	v_pk_fma_f32 v[64:65], v[68:69], v[100:101], v[64:65]
	v_rcp_f32_e32 v49, v49
	v_mul_f32_e32 v98, v64, v64
	v_mul_f32_e32 v99, v65, v65
	v_fmaak_f32 v98, v252, v98, 0x40135761
	v_fmaak_f32 v99, v252, v99, 0x40135761
	v_mul_f32_e32 v98, v64, v98
	v_mul_f32_e32 v99, v65, v99
	v_exp_f32_e32 v98, v98
	v_exp_f32_e32 v99, v99
	v_pk_fma_f32 v[48:49], v[62:63], v[48:49], v[62:63] neg_lo:[1,0,0] neg_hi:[1,0,0]
	s_waitcnt vmcnt(0)
	v_lshlrev_b32_e32 v62, 16, v54
	v_add_f32_e32 v98, 1.0, v98
	v_add_f32_e32 v99, 1.0, v99
	v_rcp_f32_e32 v98, v98
	v_rcp_f32_e32 v99, v99
	v_pk_mul_f32 v[42:43], v[42:43], v[48:49]
	v_and_b32_e32 v63, 0xffff0000, v54
	v_cvt_pk_bf16_f32 v48, v42, v43
	v_pk_fma_f32 v[42:43], v[64:65], v[98:99], v[64:65] neg_lo:[1,0,0] neg_hi:[1,0,0]
	s_nop 0
	v_pk_mul_f32 v[42:43], v[44:45], v[42:43]
	v_lshlrev_b32_e32 v44, 16, v58
	v_cvt_pk_bf16_f32 v49, v42, v43
	global_store_dwordx4 v[158:159], v[46:49], off offset:256
	v_lshlrev_b32_e32 v42, 16, v50
	v_and_b32_e32 v43, 0xffff0000, v50
	v_lshlrev_b32_e32 v46, 16, v51
	v_and_b32_e32 v47, 0xffff0000, v51
	v_lshlrev_b32_e32 v48, 16, v59
	v_and_b32_e32 v49, 0xffff0000, v59
	v_pk_fma_f32 v[46:47], v[84:85], v[46:47], v[92:93]
	v_lshlrev_b32_e32 v50, 16, v55
	v_and_b32_e32 v51, 0xffff0000, v55
	v_pk_fma_f32 v[46:47], v[88:89], v[48:49], v[46:47]
	v_and_b32_e32 v45, 0xffff0000, v58
	v_pk_fma_f32 v[50:51], v[96:97], v[50:51], v[46:47]
	v_pk_fma_f32 v[42:43], v[82:83], v[42:43], v[90:91]
	v_mul_f32_e32 v46, v50, v50
	v_fmaak_f32 v46, v252, v46, 0x40135761
	v_mul_f32_e32 v47, v51, v51
	v_mul_f32_e32 v46, v50, v46
	v_fmaak_f32 v47, v252, v47, 0x40135761
	v_mul_f32_e32 v47, v51, v47
	v_exp_f32_e32 v46, v46
	v_exp_f32_e32 v47, v47
	v_mad_i64_i32 v[58:59], s[0:1], v143, s60, v[112:113]
	v_add_f32_e32 v46, 1.0, v46
	v_pk_fma_f32 v[42:43], v[86:87], v[44:45], v[42:43]
	v_rcp_f32_e32 v54, v46
	v_add_f32_e32 v46, 1.0, v47
	v_lshl_add_u64 v[48:49], v[58:59], 0, v[146:147]
	v_pk_fma_f32 v[42:43], v[94:95], v[62:63], v[42:43]
	v_rcp_f32_e32 v55, v46
	v_lshl_add_u64 v[46:47], v[58:59], 0, v[114:115]
	v_lshl_add_u64 v[62:63], v[48:49], 0, v[114:115]
	v_lshl_add_u64 v[58:59], v[58:59], 0, v[150:151]
	global_load_dwordx4 v[46:49], v[46:47], off
	s_nop 0
	global_load_dwordx4 v[62:65], v[62:63], off
	v_lshl_add_u64 v[58:59], v[58:59], 0, v[114:115]
	global_load_dwordx4 v[98:101], v[58:59], off
	v_mul_f32_e32 v44, v42, v42
	v_mul_f32_e32 v45, v43, v43
	v_fmaak_f32 v44, v252, v44, 0x40135761
	v_fmaak_f32 v45, v252, v45, 0x40135761
	v_mul_f32_e32 v44, v42, v44
	v_mul_f32_e32 v45, v43, v45
	v_exp_f32_e32 v44, v44
	v_exp_f32_e32 v45, v45
	v_add_f32_e32 v44, 1.0, v44
	v_add_f32_e32 v45, 1.0, v45
	v_rcp_f32_e32 v44, v44
	v_rcp_f32_e32 v45, v45
	s_nop 0
; DI float bflo(unsigned w) { return __uint_as_float(w << 16); }
; DI float gelu_tanh(float v) {
;     const float uu = 0.7978845608028654f * (v + 0.044715f * v * v * v);
;     const float e = __builtin_amdgcn_exp2f(2.8853900817779268f * uu);
;     return v - v * __builtin_amdgcn_rcpf(e + 1.0f);
; }
;     DI void operator()(const AccT& acc, const Unit& u, int wr, int wc, int fr, int fq) const {
;     ...
;             for (int aim = 0; aim < 4; ++aim) { const int ai = aim >> 1, mb = (aim & 1) * 2;
;                 u32x4 a0[4], a1[4], a2[4];
; #pragma unroll
;                 for (int m = mb; m < mb + 2; ++m) {
;                     const int row = rowbase + ai * 128 + m * 16; const int sq = row & (SEQ - 1);
;                     const bf16_t* pa = A + (size_t)row * FF + col;
;                     a0[m] = *(const u32x4*)pa;
;                     a1[m] = *(const u32x4*)(pa - (sq >= 1 ? FF : 0));
;                     a2[m] = *(const u32x4*)(pa - (sq >= 2 ? 2 * FF : 0));
;                 }
; #pragma unroll
;                 for (int m = mb; m < mb + 2; ++m) {
;                     const int row = rowbase + ai * 128 + m * 16; const int sq = row & (SEQ - 1);
;                     const float k1 = sq >= 1 ? 1.0f : 0.0f, k2 = sq >= 2 ? 1.0f : 0.0f;
;                     const u32x4 x0 = a0[m], x1 = a1[m], x2 = a2[m];
;                     const float f0[8] = {bflo(x0.x), bfhi(x0.x), bflo(x0.y), bfhi(x0.y), bflo(x0.z), bfhi(x0.z), bflo(x0.w), bfhi(x0.w)};
;                     const float f1[8] = {bflo(x1.x), bfhi(x1.x), bflo(x1.y), bfhi(x1.y), bflo(x1.z), bfhi(x1.z), bflo(x1.w), bfhi(x1.w)};
;                     const float f2[8] = {bflo(x2.x), bfhi(x2.x), bflo(x2.y), bfhi(x2.y), bflo(x2.z), bfhi(x2.z), bflo(x2.w), bfhi(x2.w)};
;                     f32x4 o0, o1;
; #pragma unroll
;                     for (int j = 0; j < 4; ++j) {
;                         const float c0 = cb[0][j] + w0[0][j] * f0[j] + k1 * (w1[0][j] * f1[j]) + k2 * (w2[0][j] * f2[j]);
;                         const float c1 = cb[1][j] + w0[1][j] * f0[4 + j] + k1 * (w1[1][j] * f1[4 + j]) + k2 * (w2[1][j] * f2[4 + j]);
;                         o0[j] = gelu_tanh(c0) * acc[ai][bj][m][0][j]; o1[j] = gelu_tanh(c1) * acc[ai][bj][m][1][j];
;                     }
;                     *(u32x4*)(ACT + (size_t)row * FF + col) = pack8(o0, o1);
;                 }
	v_pk_fma_f32 v[42:43], v[42:43], v[44:45], v[42:43] neg_lo:[1,0,0] neg_hi:[1,0,0]
	s_nop 0
	v_pk_mul_f32 v[38:39], v[38:39], v[42:43]
	v_pk_fma_f32 v[42:43], v[50:51], v[54:55], v[50:51] neg_lo:[1,0,0] neg_hi:[1,0,0]
	v_lshlrev_b32_e32 v44, 16, v60
	v_pk_mul_f32 v[40:41], v[40:41], v[42:43]
	v_lshlrev_b32_e32 v42, 16, v52
	v_and_b32_e32 v43, 0xffff0000, v52
	v_and_b32_e32 v45, 0xffff0000, v60
	v_pk_fma_f32 v[42:43], v[70:71], v[42:43], v[74:75]
	v_lshlrev_b32_e32 v50, 16, v56
	v_and_b32_e32 v51, 0xffff0000, v56
	v_pk_fma_f32 v[42:43], v[78:79], v[44:45], v[42:43]
	v_cvt_pk_bf16_f32 v38, v38, v39
	v_pk_fma_f32 v[42:43], v[66:67], v[50:51], v[42:43]
	v_lshlrev_b32_e32 v50, 16, v61
	v_mul_f32_e32 v39, v42, v42
	v_fmaak_f32 v39, v252, v39, 0x40135761
	v_mul_f32_e32 v39, v42, v39
	v_exp_f32_e32 v44, v39
	v_mul_f32_e32 v39, v43, v43
	v_fmaak_f32 v39, v252, v39, 0x40135761
	v_mul_f32_e32 v39, v43, v39
	v_exp_f32_e32 v45, v39
	v_cvt_pk_bf16_f32 v39, v40, v41
	v_add_f32_e32 v40, 1.0, v44
	v_lshlrev_b32_e32 v44, 16, v53
	v_add_f32_e32 v41, 1.0, v45
	v_and_b32_e32 v45, 0xffff0000, v53
	v_and_b32_e32 v51, 0xffff0000, v61
	v_pk_fma_f32 v[44:45], v[72:73], v[44:45], v[76:77]
	v_lshlrev_b32_e32 v52, 16, v57
	v_and_b32_e32 v53, 0xffff0000, v57
	v_pk_fma_f32 v[44:45], v[80:81], v[50:51], v[44:45]
	v_rcp_f32_e32 v40, v40
	v_pk_fma_f32 v[44:45], v[68:69], v[52:53], v[44:45]
	v_rcp_f32_e32 v41, v41
	v_mul_f32_e32 v50, v44, v44
	v_mul_f32_e32 v51, v45, v45
	v_fmaak_f32 v50, v252, v50, 0x40135761
	v_fmaak_f32 v51, v252, v51, 0x40135761
	v_mul_f32_e32 v50, v44, v50
	v_mul_f32_e32 v51, v45, v51
	v_exp_f32_e32 v50, v50
	v_exp_f32_e32 v51, v51
	v_pk_fma_f32 v[40:41], v[42:43], v[40:41], v[42:43] neg_lo:[1,0,0] neg_hi:[1,0,0]
	v_add_f32_e32 v50, 1.0, v50
	v_add_f32_e32 v51, 1.0, v51
	v_rcp_f32_e32 v50, v50
	v_rcp_f32_e32 v51, v51
	v_pk_mul_f32 v[34:35], v[34:35], v[40:41]
	s_waitcnt vmcnt(2)
	v_lshlrev_b32_e32 v42, 16, v46
	v_cvt_pk_bf16_f32 v40, v34, v35
	v_pk_fma_f32 v[34:35], v[44:45], v[50:51], v[44:45] neg_lo:[1,0,0] neg_hi:[1,0,0]
	v_and_b32_e32 v43, 0xffff0000, v46
	v_pk_mul_f32 v[34:35], v[36:37], v[34:35]
	s_waitcnt vmcnt(1)
	v_lshlrev_b32_e32 v44, 16, v62
	v_cvt_pk_bf16_f32 v41, v34, v35
	v_mad_i64_i32 v[34:35], s[0:1], v145, s60, v[112:113]
	global_store_dwordx4 v[148:149], v[38:41], off offset:256
	v_and_b32_e32 v45, 0xffff0000, v62
	v_pk_fma_f32 v[42:43], v[82:83], v[42:43], v[90:91]
	v_lshl_add_u64 v[38:39], v[34:35], 0, v[114:115]
	global_load_dwordx4 v[34:37], v[38:39], off
	s_waitcnt vmcnt(2)
	v_lshlrev_b32_e32 v50, 16, v98
	v_and_b32_e32 v51, 0xffff0000, v98
	v_pk_mul_f32 v[44:45], v[86:87], v[44:45]
	v_add_co_u32_e32 v40, vcc, s61, v38
	v_pk_fma_f32 v[42:43], v[144:145], v[44:45], v[42:43] op_sel_hi:[0,1,1]
	v_pk_mul_f32 v[44:45], v[94:95], v[50:51]
	v_addc_co_u32_e32 v41, vcc, -1, v39, vcc
	v_pk_fma_f32 v[50:51], v[142:143], v[44:45], v[42:43] op_sel_hi:[0,1,1]
	v_mul_f32_e32 v42, v50, v50
	v_fmaak_f32 v42, v252, v42, 0x40135761
	v_mul_f32_e32 v42, v50, v42
	v_exp_f32_e32 v46, v42
	v_mul_f32_e32 v42, v51, v51
	v_fmaak_f32 v42, v252, v42, 0x40135761
	v_mul_f32_e32 v42, v51, v42
	v_add_co_u32_e32 v38, vcc, s62, v38
	s_nop 0
	v_addc_co_u32_e32 v39, vcc, -1, v39, vcc
	v_exp_f32_e32 v52, v42
	global_load_dwordx4 v[42:45], v[40:41], off offset:-3072
	s_nop 0
	global_load_dwordx4 v[38:41], v[38:39], off offset:-2048
	v_and_b32_e32 v53, 0xffff0000, v47
	v_lshlrev_b32_e32 v54, 16, v63
	v_add_f32_e32 v58, 1.0, v52
	v_lshlrev_b32_e32 v52, 16, v47
	v_and_b32_e32 v55, 0xffff0000, v63
	v_lshlrev_b32_e32 v56, 16, v99
	v_and_b32_e32 v57, 0xffff0000, v99
	v_pk_fma_f32 v[52:53], v[84:85], v[52:53], v[92:93]
	v_pk_mul_f32 v[54:55], v[88:89], v[54:55]
	v_add_f32_e32 v46, 1.0, v46
	v_pk_fma_f32 v[52:53], v[144:145], v[54:55], v[52:53] op_sel_hi:[0,1,1]
	v_pk_mul_f32 v[54:55], v[96:97], v[56:57]
	v_rcp_f32_e32 v46, v46
	v_pk_fma_f32 v[52:53], v[142:143], v[54:55], v[52:53] op_sel_hi:[0,1,1]
	v_mul_f32_e32 v47, v52, v52
	v_fmaak_f32 v47, v252, v47, 0x40135761
	v_mul_f32_e32 v47, v52, v47
	v_exp_f32_e32 v54, v47
	v_mul_f32_e32 v47, v53, v53
	v_fmaak_f32 v47, v252, v47, 0x40135761
	v_mul_f32_e32 v47, v53, v47
	v_exp_f32_e32 v55, v47
	v_rcp_f32_e32 v47, v58
	v_add_f32_e32 v54, 1.0, v54
	v_rcp_f32_e32 v54, v54
	v_add_f32_e32 v55, 1.0, v55
	v_rcp_f32_e32 v55, v55
	v_pk_fma_f32 v[46:47], v[50:51], v[46:47], v[50:51] neg_lo:[1,0,0] neg_hi:[1,0,0]
	v_lshlrev_b32_e32 v50, 16, v64
	v_pk_mul_f32 v[30:31], v[30:31], v[46:47]
	v_pk_fma_f32 v[46:47], v[52:53], v[54:55], v[52:53] neg_lo:[1,0,0] neg_hi:[1,0,0]
	v_and_b32_e32 v51, 0xffff0000, v64
	v_pk_mul_f32 v[32:33], v[32:33], v[46:47]
	v_lshlrev_b32_e32 v46, 16, v48
	v_and_b32_e32 v47, 0xffff0000, v48
	v_lshlrev_b32_e32 v52, 16, v100
	v_and_b32_e32 v53, 0xffff0000, v100
	v_pk_fma_f32 v[46:47], v[70:71], v[46:47], v[74:75]
	v_pk_mul_f32 v[50:51], v[78:79], v[50:51]
	v_cvt_pk_bf16_f32 v30, v30, v31
	v_pk_fma_f32 v[46:47], v[144:145], v[50:51], v[46:47] op_sel_hi:[0,1,1]
	v_pk_mul_f32 v[50:51], v[66:67], v[52:53]
	v_lshlrev_b32_e32 v52, 16, v101
	v_pk_fma_f32 v[46:47], v[142:143], v[50:51], v[46:47] op_sel_hi:[0,1,1]
	v_mul_f32_e32 v31, v46, v46
	v_fmaak_f32 v31, v252, v31, 0x40135761
	v_mul_f32_e32 v31, v46, v31
	v_exp_f32_e32 v48, v31
	v_mul_f32_e32 v31, v47, v47
	v_fmaak_f32 v31, v252, v31, 0x40135761
	v_mul_f32_e32 v31, v47, v31
	v_exp_f32_e32 v50, v31
	v_cvt_pk_bf16_f32 v31, v32, v33
	v_add_f32_e32 v32, 1.0, v48
	v_lshlrev_b32_e32 v48, 16, v49
	v_add_f32_e32 v33, 1.0, v50
	v_and_b32_e32 v49, 0xffff0000, v49
	v_lshlrev_b32_e32 v50, 16, v65
	v_and_b32_e32 v51, 0xffff0000, v65
	v_and_b32_e32 v53, 0xffff0000, v101
	v_pk_fma_f32 v[48:49], v[72:73], v[48:49], v[76:77]
	v_pk_mul_f32 v[50:51], v[80:81], v[50:51]
	v_rcp_f32_e32 v32, v32
	v_pk_fma_f32 v[48:49], v[144:145], v[50:51], v[48:49] op_sel_hi:[0,1,1]
	v_pk_mul_f32 v[50:51], v[68:69], v[52:53]
	v_rcp_f32_e32 v33, v33
	v_pk_fma_f32 v[48:49], v[142:143], v[50:51], v[48:49] op_sel_hi:[0,1,1]
	v_mul_f32_e32 v50, v48, v48
	v_mul_f32_e32 v51, v49, v49
	v_fmaak_f32 v50, v252, v50, 0x40135761
	v_fmaak_f32 v51, v252, v51, 0x40135761
	v_mul_f32_e32 v50, v48, v50
	v_mul_f32_e32 v51, v49, v51
	v_exp_f32_e32 v50, v50
	v_exp_f32_e32 v51, v51
	v_pk_fma_f32 v[32:33], v[46:47], v[32:33], v[46:47] neg_lo:[1,0,0] neg_hi:[1,0,0]
	s_waitcnt vmcnt(0)
; DI float bflo(unsigned w) { return __uint_as_float(w << 16); }
; DI float gelu_tanh(float v) {
;     const float uu = 0.7978845608028654f * (v + 0.044715f * v * v * v);
;     const float e = __builtin_amdgcn_exp2f(2.8853900817779268f * uu);
;     return v - v * __builtin_amdgcn_rcpf(e + 1.0f);
; }
;     DI void operator()(const AccT& acc, const Unit& u, int wr, int wc, int fr, int fq) const {
;     ...
;             for (int aim = 0; aim < 4; ++aim) { const int ai = aim >> 1, mb = (aim & 1) * 2;
;                 u32x4 a0[4], a1[4], a2[4];
; #pragma unroll
;                 for (int m = mb; m < mb + 2; ++m) {
;                     const int row = rowbase + ai * 128 + m * 16; const int sq = row & (SEQ - 1);
;                     const bf16_t* pa = A + (size_t)row * FF + col;
;                     a0[m] = *(const u32x4*)pa;
;                     a1[m] = *(const u32x4*)(pa - (sq >= 1 ? FF : 0));
;                     a2[m] = *(const u32x4*)(pa - (sq >= 2 ? 2 * FF : 0));
;                 }
; #pragma unroll
;                 for (int m = mb; m < mb + 2; ++m) {
;                     const int row = rowbase + ai * 128 + m * 16; const int sq = row & (SEQ - 1);
;                     const float k1 = sq >= 1 ? 1.0f : 0.0f, k2 = sq >= 2 ? 1.0f : 0.0f;
;                     const u32x4 x0 = a0[m], x1 = a1[m], x2 = a2[m];
;                     const float f0[8] = {bflo(x0.x), bfhi(x0.x), bflo(x0.y), bfhi(x0.y), bflo(x0.z), bfhi(x0.z), bflo(x0.w), bfhi(x0.w)};
;                     const float f1[8] = {bflo(x1.x), bfhi(x1.x), bflo(x1.y), bfhi(x1.y), bflo(x1.z), bfhi(x1.z), bflo(x1.w), bfhi(x1.w)};
;                     const float f2[8] = {bflo(x2.x), bfhi(x2.x), bflo(x2.y), bfhi(x2.y), bflo(x2.z), bfhi(x2.z), bflo(x2.w), bfhi(x2.w)};
;                     f32x4 o0, o1;
; #pragma unroll
;                     for (int j = 0; j < 4; ++j) {
;                         const float c0 = cb[0][j] + w0[0][j] * f0[j] + k1 * (w1[0][j] * f1[j]) + k2 * (w2[0][j] * f2[j]);
;                         const float c1 = cb[1][j] + w0[1][j] * f0[4 + j] + k1 * (w1[1][j] * f1[4 + j]) + k2 * (w2[1][j] * f2[4 + j]);
;                         o0[j] = gelu_tanh(c0) * acc[ai][bj][m][0][j]; o1[j] = gelu_tanh(c1) * acc[ai][bj][m][1][j];
;                     }
;                     *(u32x4*)(ACT + (size_t)row * FF + col) = pack8(o0, o1);
;                 }
	v_lshlrev_b32_e32 v46, 16, v38
	v_add_f32_e32 v50, 1.0, v50
	v_add_f32_e32 v51, 1.0, v51
	v_rcp_f32_e32 v50, v50
	v_rcp_f32_e32 v51, v51
	v_pk_mul_f32 v[26:27], v[26:27], v[32:33]
	v_and_b32_e32 v47, 0xffff0000, v38
	v_cvt_pk_bf16_f32 v32, v26, v27
	v_pk_fma_f32 v[26:27], v[48:49], v[50:51], v[48:49] neg_lo:[1,0,0] neg_hi:[1,0,0]
	s_nop 0
	v_pk_mul_f32 v[26:27], v[28:29], v[26:27]
	v_lshlrev_b32_e32 v28, 16, v42
	v_cvt_pk_bf16_f32 v33, v26, v27
	global_store_dwordx4 v[152:153], v[30:33], off offset:256
	v_lshlrev_b32_e32 v26, 16, v34
	v_and_b32_e32 v27, 0xffff0000, v34
	v_lshlrev_b32_e32 v30, 16, v35
	v_and_b32_e32 v31, 0xffff0000, v35
	v_lshlrev_b32_e32 v32, 16, v43
	v_and_b32_e32 v33, 0xffff0000, v43
	v_pk_fma_f32 v[30:31], v[84:85], v[30:31], v[92:93]
	v_lshlrev_b32_e32 v34, 16, v39
	v_and_b32_e32 v35, 0xffff0000, v39
	v_pk_fma_f32 v[30:31], v[88:89], v[32:33], v[30:31]
	v_and_b32_e32 v29, 0xffff0000, v42
	v_pk_fma_f32 v[34:35], v[96:97], v[34:35], v[30:31]
	v_pk_fma_f32 v[26:27], v[82:83], v[26:27], v[90:91]
	v_mul_f32_e32 v30, v34, v34
	v_fmaak_f32 v30, v252, v30, 0x40135761
	v_mul_f32_e32 v31, v35, v35
	v_mul_f32_e32 v30, v34, v30
	v_fmaak_f32 v31, v252, v31, 0x40135761
	v_mul_f32_e32 v31, v35, v31
	v_exp_f32_e32 v30, v30
	v_exp_f32_e32 v31, v31
	v_pk_fma_f32 v[26:27], v[86:87], v[28:29], v[26:27]
	v_add_f32_e32 v30, 1.0, v30
	v_rcp_f32_e32 v38, v30
	v_add_f32_e32 v30, 1.0, v31
	v_rcp_f32_e32 v39, v30
	v_mad_i64_i32 v[30:31], s[0:1], v139, s60, v[112:113]
	v_lshl_add_u64 v[42:43], v[30:31], 0, v[114:115]
	v_pk_fma_f32 v[26:27], v[94:95], v[46:47], v[26:27]
	v_add_co_u32_e32 v46, vcc, s61, v42
	v_mul_f32_e32 v28, v26, v26
	s_nop 0
	v_addc_co_u32_e32 v47, vcc, -1, v43, vcc
	global_load_dwordx4 v[30:33], v[42:43], off
	s_nop 0
	global_load_dwordx4 v[46:49], v[46:47], off offset:-3072
	v_add_co_u32_e32 v42, vcc, s62, v42
	v_mul_f32_e32 v29, v27, v27
	s_nop 0
	v_addc_co_u32_e32 v43, vcc, -1, v43, vcc
	global_load_dwordx4 v[50:53], v[42:43], off offset:-2048
	v_fmaak_f32 v28, v252, v28, 0x40135761
	v_fmaak_f32 v29, v252, v29, 0x40135761
	v_mul_f32_e32 v28, v26, v28
	v_mul_f32_e32 v29, v27, v29
	v_exp_f32_e32 v28, v28
	v_exp_f32_e32 v29, v29
	v_add_f32_e32 v28, 1.0, v28
	v_add_f32_e32 v29, 1.0, v29
	v_rcp_f32_e32 v28, v28
	v_rcp_f32_e32 v29, v29
	s_nop 0
	v_pk_fma_f32 v[26:27], v[26:27], v[28:29], v[26:27] neg_lo:[1,0,0] neg_hi:[1,0,0]
	s_nop 0
	v_pk_mul_f32 v[22:23], v[22:23], v[26:27]
	v_pk_fma_f32 v[26:27], v[34:35], v[38:39], v[34:35] neg_lo:[1,0,0] neg_hi:[1,0,0]
	v_lshlrev_b32_e32 v28, 16, v44
	v_pk_mul_f32 v[24:25], v[24:25], v[26:27]
	v_lshlrev_b32_e32 v26, 16, v36
	v_and_b32_e32 v27, 0xffff0000, v36
	v_and_b32_e32 v29, 0xffff0000, v44
	v_pk_fma_f32 v[26:27], v[70:71], v[26:27], v[74:75]
	v_lshlrev_b32_e32 v34, 16, v40
	v_and_b32_e32 v35, 0xffff0000, v40
	v_pk_fma_f32 v[26:27], v[78:79], v[28:29], v[26:27]
	v_cvt_pk_bf16_f32 v22, v22, v23
	v_pk_fma_f32 v[26:27], v[66:67], v[34:35], v[26:27]
	v_lshlrev_b32_e32 v34, 16, v45
	v_mul_f32_e32 v23, v26, v26
	v_fmaak_f32 v23, v252, v23, 0x40135761
	v_mul_f32_e32 v23, v26, v23
	v_exp_f32_e32 v28, v23
	v_mul_f32_e32 v23, v27, v27
	v_fmaak_f32 v23, v252, v23, 0x40135761
	v_mul_f32_e32 v23, v27, v23
	v_exp_f32_e32 v29, v23
	v_cvt_pk_bf16_f32 v23, v24, v25
	v_add_f32_e32 v24, 1.0, v28
	v_lshlrev_b32_e32 v28, 16, v37
	v_add_f32_e32 v25, 1.0, v29
	v_and_b32_e32 v29, 0xffff0000, v37
	v_and_b32_e32 v35, 0xffff0000, v45
	v_pk_fma_f32 v[28:29], v[72:73], v[28:29], v[76:77]
	v_lshlrev_b32_e32 v36, 16, v41
	v_and_b32_e32 v37, 0xffff0000, v41
	v_pk_fma_f32 v[28:29], v[80:81], v[34:35], v[28:29]
	v_rcp_f32_e32 v24, v24
	v_pk_fma_f32 v[28:29], v[68:69], v[36:37], v[28:29]
	v_rcp_f32_e32 v25, v25
	v_mul_f32_e32 v34, v28, v28
	v_mul_f32_e32 v35, v29, v29
	v_fmaak_f32 v34, v252, v34, 0x40135761
	v_fmaak_f32 v35, v252, v35, 0x40135761
	v_mul_f32_e32 v34, v28, v34
	v_mul_f32_e32 v35, v29, v35
	v_exp_f32_e32 v34, v34
	v_exp_f32_e32 v35, v35
	v_pk_fma_f32 v[24:25], v[26:27], v[24:25], v[26:27] neg_lo:[1,0,0] neg_hi:[1,0,0]
	s_waitcnt vmcnt(2)
	v_lshlrev_b32_e32 v26, 16, v30
	v_add_f32_e32 v34, 1.0, v34
	v_add_f32_e32 v35, 1.0, v35
	v_rcp_f32_e32 v34, v34
	v_rcp_f32_e32 v35, v35
	v_pk_mul_f32 v[14:15], v[14:15], v[24:25]
	v_and_b32_e32 v27, 0xffff0000, v30
	v_cvt_pk_bf16_f32 v24, v14, v15
	v_pk_fma_f32 v[14:15], v[28:29], v[34:35], v[28:29] neg_lo:[1,0,0] neg_hi:[1,0,0]
	s_waitcnt vmcnt(1)
	v_lshlrev_b32_e32 v28, 16, v46
	v_pk_mul_f32 v[14:15], v[16:17], v[14:15]
	v_and_b32_e32 v29, 0xffff0000, v46
	v_cvt_pk_bf16_f32 v25, v14, v15
	v_mad_i64_i32 v[14:15], s[0:1], v138, s60, v[112:113]
	global_store_dwordx4 v[136:137], v[22:25], off offset:256
	v_pk_fma_f32 v[26:27], v[82:83], v[26:27], v[90:91]
	v_and_b32_e32 v37, 0xffff0000, v31
	v_lshl_add_u64 v[22:23], v[14:15], 0, v[114:115]
	global_load_dwordx4 v[14:17], v[22:23], off
	s_waitcnt vmcnt(2)
; DI float bflo(unsigned w) { return __uint_as_float(w << 16); }
; DI float gelu_tanh(float v) {
;     const float uu = 0.7978845608028654f * (v + 0.044715f * v * v * v);
;     const float e = __builtin_amdgcn_exp2f(2.8853900817779268f * uu);
;     return v - v * __builtin_amdgcn_rcpf(e + 1.0f);
; }
;     DI void operator()(const AccT& acc, const Unit& u, int wr, int wc, int fr, int fq) const {
;     ...
;             for (int aim = 0; aim < 4; ++aim) { const int ai = aim >> 1, mb = (aim & 1) * 2;
;                 u32x4 a0[4], a1[4], a2[4];
; #pragma unroll
;                 for (int m = mb; m < mb + 2; ++m) {
;                     const int row = rowbase + ai * 128 + m * 16; const int sq = row & (SEQ - 1);
;                     const bf16_t* pa = A + (size_t)row * FF + col;
;                     a0[m] = *(const u32x4*)pa;
;                     a1[m] = *(const u32x4*)(pa - (sq >= 1 ? FF : 0));
;                     a2[m] = *(const u32x4*)(pa - (sq >= 2 ? 2 * FF : 0));
;                 }
; #pragma unroll
;                 for (int m = mb; m < mb + 2; ++m) {
;                     const int row = rowbase + ai * 128 + m * 16; const int sq = row & (SEQ - 1);
;                     const float k1 = sq >= 1 ? 1.0f : 0.0f, k2 = sq >= 2 ? 1.0f : 0.0f;
;                     const u32x4 x0 = a0[m], x1 = a1[m], x2 = a2[m];
;                     const float f0[8] = {bflo(x0.x), bfhi(x0.x), bflo(x0.y), bfhi(x0.y), bflo(x0.z), bfhi(x0.z), bflo(x0.w), bfhi(x0.w)};
;                     const float f1[8] = {bflo(x1.x), bfhi(x1.x), bflo(x1.y), bfhi(x1.y), bflo(x1.z), bfhi(x1.z), bflo(x1.w), bfhi(x1.w)};
;                     const float f2[8] = {bflo(x2.x), bfhi(x2.x), bflo(x2.y), bfhi(x2.y), bflo(x2.z), bfhi(x2.z), bflo(x2.w), bfhi(x2.w)};
;                     f32x4 o0, o1;
; #pragma unroll
;                     for (int j = 0; j < 4; ++j) {
;                         const float c0 = cb[0][j] + w0[0][j] * f0[j] + k1 * (w1[0][j] * f1[j]) + k2 * (w2[0][j] * f2[j]);
;                         const float c1 = cb[1][j] + w0[1][j] * f0[4 + j] + k1 * (w1[1][j] * f1[4 + j]) + k2 * (w2[1][j] * f2[4 + j]);
;                         o0[j] = gelu_tanh(c0) * acc[ai][bj][m][0][j]; o1[j] = gelu_tanh(c1) * acc[ai][bj][m][1][j];
;                     }
;                     *(u32x4*)(ACT + (size_t)row * FF + col) = pack8(o0, o1);
;                 }
	v_lshlrev_b32_e32 v34, 16, v50
	v_and_b32_e32 v35, 0xffff0000, v50
	v_pk_fma_f32 v[26:27], v[86:87], v[28:29], v[26:27]
	v_add_co_u32_e32 v24, vcc, s61, v22
	v_pk_fma_f32 v[34:35], v[94:95], v[34:35], v[26:27]
	s_nop 0
	v_addc_co_u32_e32 v25, vcc, -1, v23, vcc
	v_mul_f32_e32 v26, v34, v34
	v_fmaak_f32 v26, v252, v26, 0x40135761
	v_mul_f32_e32 v26, v34, v26
	v_exp_f32_e32 v30, v26
	v_mul_f32_e32 v26, v35, v35
	v_fmaak_f32 v26, v252, v26, 0x40135761
	v_mul_f32_e32 v26, v35, v26
	v_add_co_u32_e32 v22, vcc, s62, v22
	s_nop 0
	v_addc_co_u32_e32 v23, vcc, -1, v23, vcc
	v_exp_f32_e32 v36, v26
	global_load_dwordx4 v[26:29], v[24:25], off offset:-3072
	s_nop 0
	global_load_dwordx4 v[22:25], v[22:23], off offset:-2048
	v_lshlrev_b32_e32 v38, 16, v47
	v_and_b32_e32 v39, 0xffff0000, v47
	v_add_f32_e32 v42, 1.0, v36
	v_lshlrev_b32_e32 v36, 16, v31
	v_pk_fma_f32 v[36:37], v[84:85], v[36:37], v[92:93]
	v_lshlrev_b32_e32 v40, 16, v51
	v_and_b32_e32 v41, 0xffff0000, v51
	v_pk_fma_f32 v[36:37], v[88:89], v[38:39], v[36:37]
	v_add_f32_e32 v30, 1.0, v30
	v_pk_fma_f32 v[36:37], v[96:97], v[40:41], v[36:37]
	v_rcp_f32_e32 v30, v30
	v_mul_f32_e32 v31, v36, v36
	v_fmaak_f32 v31, v252, v31, 0x40135761
	v_mul_f32_e32 v31, v36, v31
	v_exp_f32_e32 v38, v31
	v_mul_f32_e32 v31, v37, v37
	v_fmaak_f32 v31, v252, v31, 0x40135761
	v_mul_f32_e32 v31, v37, v31
	v_exp_f32_e32 v39, v31
	v_rcp_f32_e32 v31, v42
	v_add_f32_e32 v38, 1.0, v38
	v_rcp_f32_e32 v38, v38
	v_add_f32_e32 v39, 1.0, v39
	v_rcp_f32_e32 v39, v39
	v_pk_fma_f32 v[30:31], v[34:35], v[30:31], v[34:35] neg_lo:[1,0,0] neg_hi:[1,0,0]
	v_lshlrev_b32_e32 v34, 16, v48
	v_pk_mul_f32 v[18:19], v[18:19], v[30:31]
	v_pk_fma_f32 v[30:31], v[36:37], v[38:39], v[36:37] neg_lo:[1,0,0] neg_hi:[1,0,0]
	v_and_b32_e32 v35, 0xffff0000, v48
	v_pk_mul_f32 v[20:21], v[20:21], v[30:31]
	v_lshlrev_b32_e32 v30, 16, v32
	v_and_b32_e32 v31, 0xffff0000, v32
	v_pk_fma_f32 v[30:31], v[70:71], v[30:31], v[74:75]
	v_lshlrev_b32_e32 v36, 16, v52
	v_and_b32_e32 v37, 0xffff0000, v52
	v_pk_fma_f32 v[30:31], v[78:79], v[34:35], v[30:31]
	v_cvt_pk_bf16_f32 v18, v18, v19
	v_pk_fma_f32 v[30:31], v[66:67], v[36:37], v[30:31]
	v_and_b32_e32 v35, 0xffff0000, v49
	v_mul_f32_e32 v19, v30, v30
	v_fmaak_f32 v19, v252, v19, 0x40135761
	v_mul_f32_e32 v19, v30, v19
	v_exp_f32_e32 v32, v19
	v_mul_f32_e32 v19, v31, v31
	v_fmaak_f32 v19, v252, v19, 0x40135761
	v_mul_f32_e32 v19, v31, v19
	v_exp_f32_e32 v34, v19
	v_cvt_pk_bf16_f32 v19, v20, v21
	v_add_f32_e32 v20, 1.0, v32
	v_lshlrev_b32_e32 v32, 16, v33
	v_and_b32_e32 v33, 0xffff0000, v33
	v_add_f32_e32 v21, 1.0, v34
	v_lshlrev_b32_e32 v34, 16, v49
	v_pk_fma_f32 v[32:33], v[72:73], v[32:33], v[76:77]
	v_lshlrev_b32_e32 v36, 16, v53
	v_and_b32_e32 v37, 0xffff0000, v53
	v_pk_fma_f32 v[32:33], v[80:81], v[34:35], v[32:33]
	v_rcp_f32_e32 v20, v20
	v_pk_fma_f32 v[32:33], v[68:69], v[36:37], v[32:33]
	v_rcp_f32_e32 v21, v21
	v_mul_f32_e32 v34, v32, v32
	v_mul_f32_e32 v35, v33, v33
	v_fmaak_f32 v34, v252, v34, 0x40135761
	v_fmaak_f32 v35, v252, v35, 0x40135761
	v_mul_f32_e32 v34, v32, v34
	v_mul_f32_e32 v35, v33, v35
	v_exp_f32_e32 v34, v34
	v_exp_f32_e32 v35, v35
	v_pk_fma_f32 v[20:21], v[30:31], v[20:21], v[30:31] neg_lo:[1,0,0] neg_hi:[1,0,0]
	s_waitcnt vmcnt(0)
; DI float bflo(unsigned w) { return __uint_as_float(w << 16); }
; DI float gelu_tanh(float v) {
;     const float uu = 0.7978845608028654f * (v + 0.044715f * v * v * v);
;     const float e = __builtin_amdgcn_exp2f(2.8853900817779268f * uu);
;     return v - v * __builtin_amdgcn_rcpf(e + 1.0f);
; }
;     DI void operator()(const AccT& acc, const Unit& u, int wr, int wc, int fr, int fq) const {
;     ...
;             for (int aim = 0; aim < 4; ++aim) { const int ai = aim >> 1, mb = (aim & 1) * 2;
;                 u32x4 a0[4], a1[4], a2[4];
; #pragma unroll
;                 for (int m = mb; m < mb + 2; ++m) {
;                     const int row = rowbase + ai * 128 + m * 16; const int sq = row & (SEQ - 1);
;                     const bf16_t* pa = A + (size_t)row * FF + col;
;                     a0[m] = *(const u32x4*)pa;
;                     a1[m] = *(const u32x4*)(pa - (sq >= 1 ? FF : 0));
;                     a2[m] = *(const u32x4*)(pa - (sq >= 2 ? 2 * FF : 0));
;                 }
; #pragma unroll
;                 for (int m = mb; m < mb + 2; ++m) {
;                     const int row = rowbase + ai * 128 + m * 16; const int sq = row & (SEQ - 1);
;                     const float k1 = sq >= 1 ? 1.0f : 0.0f, k2 = sq >= 2 ? 1.0f : 0.0f;
;                     const u32x4 x0 = a0[m], x1 = a1[m], x2 = a2[m];
;                     const float f0[8] = {bflo(x0.x), bfhi(x0.x), bflo(x0.y), bfhi(x0.y), bflo(x0.z), bfhi(x0.z), bflo(x0.w), bfhi(x0.w)};
;                     const float f1[8] = {bflo(x1.x), bfhi(x1.x), bflo(x1.y), bfhi(x1.y), bflo(x1.z), bfhi(x1.z), bflo(x1.w), bfhi(x1.w)};
;                     const float f2[8] = {bflo(x2.x), bfhi(x2.x), bflo(x2.y), bfhi(x2.y), bflo(x2.z), bfhi(x2.z), bflo(x2.w), bfhi(x2.w)};
;                     f32x4 o0, o1;
; #pragma unroll
;                     for (int j = 0; j < 4; ++j) {
;                         const float c0 = cb[0][j] + w0[0][j] * f0[j] + k1 * (w1[0][j] * f1[j]) + k2 * (w2[0][j] * f2[j]);
;                         const float c1 = cb[1][j] + w0[1][j] * f0[4 + j] + k1 * (w1[1][j] * f1[4 + j]) + k2 * (w2[1][j] * f2[4 + j]);
;                         o0[j] = gelu_tanh(c0) * acc[ai][bj][m][0][j]; o1[j] = gelu_tanh(c1) * acc[ai][bj][m][1][j];
;                     }
;                     *(u32x4*)(ACT + (size_t)row * FF + col) = pack8(o0, o1);
;                 }
	v_lshlrev_b32_e32 v30, 16, v22
	v_add_f32_e32 v34, 1.0, v34
	v_add_f32_e32 v35, 1.0, v35
	v_rcp_f32_e32 v34, v34
	v_rcp_f32_e32 v35, v35
	v_pk_mul_f32 v[10:11], v[10:11], v[20:21]
	v_and_b32_e32 v31, 0xffff0000, v22
	v_cvt_pk_bf16_f32 v20, v10, v11
	v_pk_fma_f32 v[10:11], v[32:33], v[34:35], v[32:33] neg_lo:[1,0,0] neg_hi:[1,0,0]
	s_andn2_b64 vcc, exec, s[36:37]
	v_pk_mul_f32 v[10:11], v[12:13], v[10:11]
	v_lshlrev_b32_e32 v12, 16, v26
	v_cvt_pk_bf16_f32 v21, v10, v11
	v_lshlrev_b32_e32 v10, 16, v14
	v_and_b32_e32 v11, 0xffff0000, v14
	v_and_b32_e32 v13, 0xffff0000, v26
	v_pk_fma_f32 v[10:11], v[82:83], v[10:11], v[90:91]
	v_lshlrev_b32_e32 v14, 16, v15
	v_and_b32_e32 v15, 0xffff0000, v15
	v_pk_fma_f32 v[10:11], v[86:87], v[12:13], v[10:11]
	global_store_dwordx4 v[134:135], v[18:21], off offset:256
	v_pk_fma_f32 v[14:15], v[84:85], v[14:15], v[92:93]
	v_pk_fma_f32 v[10:11], v[94:95], v[30:31], v[10:11]
	v_lshlrev_b32_e32 v18, 16, v27
	v_and_b32_e32 v19, 0xffff0000, v27
	v_lshlrev_b32_e32 v20, 16, v23
	v_and_b32_e32 v21, 0xffff0000, v23
	v_pk_fma_f32 v[14:15], v[88:89], v[18:19], v[14:15]
	v_mul_f32_e32 v12, v10, v10
	v_mul_f32_e32 v13, v11, v11
	v_pk_fma_f32 v[14:15], v[96:97], v[20:21], v[14:15]
	v_fmaak_f32 v12, v252, v12, 0x40135761
	v_fmaak_f32 v13, v252, v13, 0x40135761
	v_mul_f32_e32 v18, v14, v14
	v_mul_f32_e32 v19, v15, v15
	v_mul_f32_e32 v12, v10, v12
	v_mul_f32_e32 v13, v11, v13
	v_fmaak_f32 v18, v252, v18, 0x40135761
	v_fmaak_f32 v19, v252, v19, 0x40135761
	v_mul_f32_e32 v18, v14, v18
	v_mul_f32_e32 v19, v15, v19
	v_exp_f32_e32 v12, v12
	v_exp_f32_e32 v13, v13
	v_exp_f32_e32 v18, v18
	v_exp_f32_e32 v19, v19
	v_add_f32_e32 v12, 1.0, v12
	v_add_f32_e32 v13, 1.0, v13
	v_rcp_f32_e32 v12, v12
	v_rcp_f32_e32 v13, v13
	v_add_f32_e32 v18, 1.0, v18
	v_add_f32_e32 v19, 1.0, v19
	v_rcp_f32_e32 v18, v18
	v_rcp_f32_e32 v19, v19
	v_pk_fma_f32 v[10:11], v[10:11], v[12:13], v[10:11] neg_lo:[1,0,0] neg_hi:[1,0,0]
	v_lshlrev_b32_e32 v12, 16, v28
	v_pk_mul_f32 v[6:7], v[6:7], v[10:11]
	v_pk_fma_f32 v[10:11], v[14:15], v[18:19], v[14:15] neg_lo:[1,0,0] neg_hi:[1,0,0]
	v_and_b32_e32 v13, 0xffff0000, v28
	v_pk_mul_f32 v[8:9], v[8:9], v[10:11]
	v_lshlrev_b32_e32 v10, 16, v16
	v_and_b32_e32 v11, 0xffff0000, v16
	v_pk_fma_f32 v[10:11], v[70:71], v[10:11], v[74:75]
	v_lshlrev_b32_e32 v14, 16, v24
	v_and_b32_e32 v15, 0xffff0000, v24
	v_pk_fma_f32 v[10:11], v[78:79], v[12:13], v[10:11]
	v_cvt_pk_bf16_f32 v6, v6, v7
	v_pk_fma_f32 v[10:11], v[66:67], v[14:15], v[10:11]
	v_lshlrev_b32_e32 v14, 16, v29
	v_mul_f32_e32 v7, v10, v10
	v_fmaak_f32 v7, v252, v7, 0x40135761
	v_mul_f32_e32 v7, v10, v7
	v_exp_f32_e32 v12, v7
	v_mul_f32_e32 v7, v11, v11
	v_fmaak_f32 v7, v252, v7, 0x40135761
	v_mul_f32_e32 v7, v11, v7
	v_exp_f32_e32 v13, v7
	v_cvt_pk_bf16_f32 v7, v8, v9
	v_add_f32_e32 v8, 1.0, v12
	v_lshlrev_b32_e32 v12, 16, v17
	v_add_f32_e32 v9, 1.0, v13
	v_and_b32_e32 v13, 0xffff0000, v17
	v_and_b32_e32 v15, 0xffff0000, v29
	v_pk_fma_f32 v[12:13], v[72:73], v[12:13], v[76:77]
	v_lshlrev_b32_e32 v16, 16, v25
	v_and_b32_e32 v17, 0xffff0000, v25
	v_pk_fma_f32 v[12:13], v[80:81], v[14:15], v[12:13]
	v_rcp_f32_e32 v8, v8
	v_pk_fma_f32 v[12:13], v[68:69], v[16:17], v[12:13]
	v_rcp_f32_e32 v9, v9
	v_mul_f32_e32 v14, v12, v12
	v_mul_f32_e32 v15, v13, v13
	v_fmaak_f32 v14, v252, v14, 0x40135761
	v_fmaak_f32 v15, v252, v15, 0x40135761
	v_mul_f32_e32 v14, v12, v14
	v_mul_f32_e32 v15, v13, v15
	v_exp_f32_e32 v14, v14
	v_exp_f32_e32 v15, v15
	v_pk_fma_f32 v[8:9], v[10:11], v[8:9], v[10:11] neg_lo:[1,0,0] neg_hi:[1,0,0]
	s_mov_b64 s[0:1], -1
	v_add_f32_e32 v14, 1.0, v14
	v_add_f32_e32 v15, 1.0, v15
	v_rcp_f32_e32 v14, v14
	v_rcp_f32_e32 v15, v15
	v_pk_mul_f32 v[2:3], v[2:3], v[8:9]
	s_nop 0
	v_cvt_pk_bf16_f32 v8, v2, v3
	v_pk_fma_f32 v[2:3], v[12:13], v[14:15], v[12:13] neg_lo:[1,0,0] neg_hi:[1,0,0]
	s_nop 0
	v_pk_mul_f32 v[2:3], v[4:5], v[2:3]
	s_nop 0
	v_cvt_pk_bf16_f32 v9, v2, v3
	global_store_dwordx4 v[110:111], v[6:9], off offset:256
	s_cbranch_vccnz .LBB0_540
	s_andn2_b64 vcc, exec, s[10:11]
	s_cbranch_vccnz .LBB0_539
	s_barrier
	s_branch .LBB0_539

; __global__ void __launch_bounds__(512, 2) mega(Params p) {
;     extern __shared__ __attribute__((aligned(16))) unsigned char shm[];
	.amdhsa_kernel _Z4mega6Params
		.amdhsa_group_segment_fixed_size 0
		.amdhsa_private_segment_fixed_size 0
		.amdhsa_kernarg_size 440
		.amdhsa_user_sgpr_count 2
		.amdhsa_user_sgpr_dispatch_ptr 0
		.amdhsa_user_sgpr_queue_ptr 0
		.amdhsa_user_sgpr_kernarg_segment_ptr 1
		.amdhsa_user_sgpr_dispatch_id 0
		.amdhsa_user_sgpr_kernarg_preload_length 0
		.amdhsa_user_sgpr_kernarg_preload_offset 0
		.amdhsa_user_sgpr_private_segment_size 0
		.amdhsa_uses_dynamic_stack 0
		.amdhsa_enable_private_segment 0
		.amdhsa_system_sgpr_workgroup_id_x 1
		.amdhsa_system_sgpr_workgroup_id_y 0
		.amdhsa_system_sgpr_workgroup_id_z 0
		.amdhsa_system_sgpr_workgroup_info 0
		.amdhsa_system_vgpr_workitem_id 2
		.amdhsa_next_free_vgpr 256
		.amdhsa_next_free_sgpr 102
		.amdhsa_accum_offset 256
		.amdhsa_reserve_vcc 1
		.amdhsa_float_round_mode_32 0
		.amdhsa_float_round_mode_16_64 0
		.amdhsa_float_denorm_mode_32 3
		.amdhsa_float_denorm_mode_16_64 3
		.amdhsa_dx10_clamp 1
		.amdhsa_ieee_mode 1
		.amdhsa_fp16_overflow 0
		.amdhsa_tg_split 0
		.amdhsa_exception_fp_ieee_invalid_op 0
		.amdhsa_exception_fp_denorm_src 0
		.amdhsa_exception_fp_ieee_div_zero 0
		.amdhsa_exception_fp_ieee_overflow 0
		.amdhsa_exception_fp_ieee_underflow 0
		.amdhsa_exception_fp_ieee_inexact 0
		.amdhsa_exception_int_div_zero 0
	.end_amdhsa_kernel

amdhsa.kernels:
  - .agpr_count:     0
    .args:
      - .offset:         0
        .size:           184
        .value_kind:     by_value
      - .offset:         184
        .size:           4
        .value_kind:     hidden_block_count_x
      - .offset:         188
        .size:           4
        .value_kind:     hidden_block_count_y
      - .offset:         192
        .size:           4
        .value_kind:     hidden_block_count_z
      - .offset:         196
        .size:           2
        .value_kind:     hidden_group_size_x
      - .offset:         198
        .size:           2
        .value_kind:     hidden_group_size_y
      - .offset:         200
        .size:           2
        .value_kind:     hidden_group_size_z
      - .offset:         202
        .size:           2
        .value_kind:     hidden_remainder_x
      - .offset:         204
        .size:           2
        .value_kind:     hidden_remainder_y
      - .offset:         206
        .size:           2
        .value_kind:     hidden_remainder_z
      - .offset:         224
        .size:           8
        .value_kind:     hidden_global_offset_x
      - .offset:         232
        .size:           8
        .value_kind:     hidden_global_offset_y
      - .offset:         240
        .size:           8
        .value_kind:     hidden_global_offset_z
      - .offset:         248
        .size:           2
        .value_kind:     hidden_grid_dims
      - .offset:         272
        .size:           8
        .value_kind:     hidden_multigrid_sync_arg
      - .offset:         304
        .size:           4
        .value_kind:     hidden_dynamic_lds_size
    .group_segment_fixed_size: 0
    .kernarg_segment_align: 8
    .kernarg_segment_size: 440
    .language:       OpenCL C
    .language_version:
      - 2
      - 0
    .max_flat_workgroup_size: 512
    .name:           _Z4mega6Params
    .private_segment_fixed_size: 0
    .sgpr_count:     108
    .sgpr_spill_count: 101
    .symbol:         _Z4mega6Params.kd
    .uniform_work_group_size: 1
    .uses_dynamic_stack: false
    .vgpr_count:     256
    .vgpr_spill_count: 0
    .wavefront_size: 64
